# raise wave priority (s_setprio 1) inside the three GEMM main loops so the MFMA/DMA waves win issue against the other block's VALU-heavy epilogue; peerq uses the 2-step DMA lead loop too
# speedup vs baseline: 1.0043x; 1.0043x over previous
; DI int otid() { int t; asm volatile("v_mov_b32 %0, %1" : "=v"(t) : "v"((int)threadIdx.x)); return t; }
; template <bool RESCALE, bool SWAP>
; DI void gemm_mainloop_glds(const bf16_t* __restrict__ A, const bf16_t* __restrict__ Bt, int m0, int n0, char* lds,
;                            f32x16 (&acc)[2][2], const float* ratio_lds) {
;   constexpr int K = 1024, NK = K / 64, OPB = 16384, STB = 2 * OPB;
;   const int tid = otid(), lane = tid & 63, w = tid >> 6, wm = w >> 1, wn = w & 1, l31 = lane & 31, h = lane >> 5;
;   const int lr = lane >> 3, csrc = (lane & 7) ^ (4 * (w & 1) + (lr >> 1));
;   const bf16_t* ag = A + (size_t)(m0 + 8 * w + lr) * K + csrc * 8;
;   const bf16_t* bg = Bt + (size_t)(n0 + 8 * w + lr) * K + csrc * 8;
;   const unsigned lbase = (unsigned)(size_t)lds + (unsigned)w * 1024u;
;   const int swz = (l31 >> 1) & 7;
;   const char* fa = lds + (64 * wm + l31) * 128;
;   const char* fb = lds + OPB + (64 * wn + l31) * 128;
;   int fo[4];
; #pragma unroll
;   for (int s_ = 0; s_ < 4; ++s_) fo[s_] = ((2 * s_ + h) ^ swz) * 16;
;   f32x16 c00, c01, c10, c11;
; #pragma unroll
;   for (int r = 0; r < 16; ++r) { c00[r] = 0.f; c01[r] = 0.f; c10[r] = 0.f; c11[r] = 0.f; }
;     ...
;   D_ISSUE(0, 0);
;   __syncthreads();
; #pragma unroll 1
;   for (int kt = 0; kt < NK; kt += 2) {
;     D_ISSUE(1, kt + 1);
.LBB0_178:
	s_mov_b64 s[76:77], -1
	s_and_b64 vcc, exec, s[38:39]
	s_cbranch_vccz .LBB0_170
	s_lshl_b32 s84, s24, 7
	s_lshl_b32 s76, s85, 7
	s_cmp_eq_u32 s85, 5
	s_cselect_b64 s[38:39], -1, 0
	s_cmp_gt_i32 s85, 13
	s_cselect_b64 s[78:79], -1, 0
	s_or_b64 vcc, s[38:39], s[78:79]
	s_mov_b64 s[78:79], -1
	s_and_b64 vcc, exec, vcc
	s_cbranch_vccnz .LBB0_185
	s_setprio 1
	v_readlane_b32 s78, v182, 19
	v_readlane_b32 s79, v182, 20
	v_lshrrev_b32_e32 v119, 3, v118
	v_lshrrev_b32_e32 v120, 6, v118
	v_and_b32_e32 v121, 1, v120
	v_bfe_u32 v122, v118, 4, 2
	v_lshl_or_b32 v122, v121, 2, v122
	v_and_b32_e32 v123, 7, v118
	v_xor_b32_e32 v122, v122, v123
	v_lshlrev_b32_e32 v124, 10, v120
	v_add_u32_e32 v126, s84, v119
	v_add_u32_e32 v128, s76, v119
	v_readfirstlane_b32 s86, v124
	v_lshlrev_b32_e32 v126, 11, v126
	v_lshlrev_b32_e32 v128, 11, v128
	v_lshl_or_b32 v126, v122, 4, v126
	v_lshl_or_b32 v128, v122, 4, v128
	v_mov_b32_e32 v127, 0
	v_mov_b32_e32 v129, 0
	v_lshl_add_u64 v[90:91], v[126:127], 0, s[78:79]
	v_lshl_add_u64 v[92:93], v[128:129], 0, s[20:21]
	v_lshl_add_u64 v[94:95], v[90:91], 0, s[34:35]
	v_lshl_add_u64 v[102:103], v[90:91], 0, s[40:41]
	v_lshl_add_u64 v[106:107], v[90:91], 0, s[42:43]
	v_lshl_add_u64 v[96:97], v[92:93], 0, s[34:35]
	v_lshl_add_u64 v[104:105], v[92:93], 0, s[40:41]
	v_lshl_add_u64 v[108:109], v[92:93], 0, s[42:43]
	v_mov_b32_e32 v130, 0x80
	v_mov_b32_e32 v131, 0
	s_mov_b32 m0, s86
	s_nop 0
	global_load_lds_dwordx4 v[90:91], off
	s_add_u32 m0, s86, 0x4000
	s_nop 0
	global_load_lds_dwordx4 v[92:93], off
	s_add_u32 m0, s86, 0x1000
	s_nop 0
	global_load_lds_dwordx4 v[94:95], off
	s_add_u32 m0, s86, 0x5000
	s_nop 0
	global_load_lds_dwordx4 v[96:97], off
	s_add_u32 m0, s86, 0x2000
	s_nop 0
	global_load_lds_dwordx4 v[102:103], off
	s_add_u32 m0, s86, 0x6000
	s_nop 0
	global_load_lds_dwordx4 v[104:105], off
	s_add_u32 m0, s86, 0x3000
	s_nop 0
	global_load_lds_dwordx4 v[106:107], off
	s_add_u32 m0, s86, 0x7000
	s_nop 0
	global_load_lds_dwordx4 v[108:109], off
	s_add_u32 m0, s86, 0x8000
	v_lshl_add_u64 v[90:91], v[130:131], 0, v[90:91]
	global_load_lds_dwordx4 v[90:91], off
	s_add_u32 m0, s86, 0xc000
	v_lshl_add_u64 v[92:93], v[130:131], 0, v[92:93]
	global_load_lds_dwordx4 v[92:93], off
	s_add_u32 m0, s86, 0x9000
	v_lshl_add_u64 v[94:95], v[130:131], 0, v[94:95]
	global_load_lds_dwordx4 v[94:95], off
	s_add_u32 m0, s86, 0xd000
	v_lshl_add_u64 v[96:97], v[130:131], 0, v[96:97]
	global_load_lds_dwordx4 v[96:97], off
	s_add_u32 m0, s86, 0xa000
	v_lshl_add_u64 v[102:103], v[130:131], 0, v[102:103]
	global_load_lds_dwordx4 v[102:103], off
	s_add_u32 m0, s86, 0xe000
	v_lshl_add_u64 v[104:105], v[130:131], 0, v[104:105]
	global_load_lds_dwordx4 v[104:105], off
	s_add_u32 m0, s86, 0xb000
	v_lshl_add_u64 v[106:107], v[130:131], 0, v[106:107]
	global_load_lds_dwordx4 v[106:107], off
	s_add_u32 m0, s86, 0xf000
	v_lshl_add_u64 v[108:109], v[130:131], 0, v[108:109]
	global_load_lds_dwordx4 v[108:109], off
	v_and_b32_e32 v119, 31, v118
	v_bfe_u32 v120, v118, 5, 1
	v_bfe_u32 v121, v118, 1, 3
	v_lshrrev_b32_e32 v122, 7, v118
	v_bfe_u32 v123, v118, 6, 1
	v_lshl_or_b32 v122, v122, 6, v119
	v_lshl_or_b32 v123, v123, 6, v119
	v_lshlrev_b32_e32 v122, 7, v122
	v_lshlrev_b32_e32 v123, 7, v123
	v_or_b32_e32 v124, 0, v120
	v_xor_b32_e32 v124, v124, v121
	v_lshl_add_u32 v110, v124, 4, v122
	v_lshl_add_u32 v114, v124, 4, v123
	v_or_b32_e32 v124, 2, v120
	v_xor_b32_e32 v124, v124, v121
	v_lshl_add_u32 v111, v124, 4, v122
	v_lshl_add_u32 v115, v124, 4, v123
	v_or_b32_e32 v124, 4, v120
	v_xor_b32_e32 v124, v124, v121
	v_lshl_add_u32 v112, v124, 4, v122
	v_lshl_add_u32 v116, v124, 4, v123
	v_or_b32_e32 v124, 6, v120
	v_xor_b32_e32 v124, v124, v121
	v_lshl_add_u32 v113, v124, 4, v122
	v_lshl_add_u32 v117, v124, 4, v123
	v_mov_b32_e32 v48, 0
	v_mov_b32_e32 v49, 0
	v_mov_b32_e32 v50, 0
	v_mov_b32_e32 v51, 0
	v_mov_b32_e32 v52, 0
	v_mov_b32_e32 v53, 0
	v_mov_b32_e32 v54, 0
	v_mov_b32_e32 v55, 0
	v_mov_b32_e32 v56, 0
	v_mov_b32_e32 v57, 0
	v_mov_b32_e32 v58, 0
	v_mov_b32_e32 v59, 0
	v_mov_b32_e32 v60, 0
	v_mov_b32_e32 v61, 0
	v_mov_b32_e32 v62, 0
	v_mov_b32_e32 v63, 0
	v_mov_b32_e32 v32, 0
	v_mov_b32_e32 v33, 0
	v_mov_b32_e32 v34, 0
	v_mov_b32_e32 v35, 0
	v_mov_b32_e32 v36, 0
	v_mov_b32_e32 v37, 0
	v_mov_b32_e32 v38, 0
	v_mov_b32_e32 v39, 0
	v_mov_b32_e32 v40, 0
	v_mov_b32_e32 v41, 0
	v_mov_b32_e32 v42, 0
	v_mov_b32_e32 v43, 0
	v_mov_b32_e32 v44, 0
	v_mov_b32_e32 v45, 0
	v_mov_b32_e32 v46, 0
	v_mov_b32_e32 v47, 0
	v_mov_b32_e32 v16, 0
	v_mov_b32_e32 v17, 0
	v_mov_b32_e32 v18, 0
	v_mov_b32_e32 v19, 0
	v_mov_b32_e32 v20, 0
	v_mov_b32_e32 v21, 0
	v_mov_b32_e32 v22, 0
	v_mov_b32_e32 v23, 0
	v_mov_b32_e32 v24, 0
	v_mov_b32_e32 v25, 0
	v_mov_b32_e32 v26, 0
	v_mov_b32_e32 v27, 0
	v_mov_b32_e32 v28, 0
	v_mov_b32_e32 v29, 0
	v_mov_b32_e32 v30, 0
	v_mov_b32_e32 v31, 0
	v_mov_b32_e32 v0, 0
	v_mov_b32_e32 v1, 0
	v_mov_b32_e32 v2, 0
	v_mov_b32_e32 v3, 0
	v_mov_b32_e32 v4, 0
	v_mov_b32_e32 v5, 0
	v_mov_b32_e32 v6, 0
	v_mov_b32_e32 v7, 0
	v_mov_b32_e32 v8, 0
	v_mov_b32_e32 v9, 0
	v_mov_b32_e32 v10, 0
	v_mov_b32_e32 v11, 0
	v_mov_b32_e32 v12, 0
	v_mov_b32_e32 v13, 0
	v_mov_b32_e32 v14, 0
	v_mov_b32_e32 v15, 0
	s_mov_b32 s77, 0
	s_waitcnt vmcnt(8)
	s_barrier
; DI int crow(int r, int h) { return (r & 3) + 8 * (r >> 2) + 4 * h; }
; #define D_COMPUTE(BUF) { D_MMA1(BUF, 0) D_MMA1(BUF, 1) D_MMA1(BUF, 2) D_MMA1(BUF, 3) }
; template <bool RESCALE, bool SWAP>
; DI void gemm_mainloop_glds(const bf16_t* __restrict__ A, const bf16_t* __restrict__ Bt, int m0, int n0, char* lds,
;                            f32x16 (&acc)[2][2], const float* ratio_lds) {
;     ...
;   for (int kt = 0; kt < NK; kt += 2) {
;     D_ISSUE(1, kt + 1);
;     if (RESCALE) {
;       if (kt == NK / 2) {
;         if (SWAP) {
;           const float sc0_ = ratio_lds[64 * wm + l31], sc1_ = ratio_lds[64 * wm + 32 + l31];
; #pragma unroll
;           for (int r = 0; r < 16; ++r) { c00[r] *= sc0_; c10[r] *= sc0_; c01[r] *= sc1_; c11[r] *= sc1_; }
;         } else {
; #pragma unroll
;           for (int r = 0; r < 16; ++r) {
;             float sc0_ = ratio_lds[64 * wm + crow(r, h)], sc1_ = ratio_lds[64 * wm + 32 + crow(r, h)];
;             c00[r] *= sc0_; c01[r] *= sc0_; c10[r] *= sc1_; c11[r] *= sc1_;
;           }
;         }
;       }
;     }
;     D_COMPUTE(0);
;     __syncthreads();
;     if (kt + 2 < NK) D_ISSUE(0, kt + 2);
;     D_COMPUTE(1);
;     __syncthreads();
;   }
.Lgm_g1s_loop:
	ds_read_b128 v[184:187], v110
	ds_read_b128 v[188:191], v110 offset:4096
	ds_read_b128 v[192:195], v114 offset:16384
	ds_read_b128 v[196:199], v114 offset:20480
	ds_read_b128 v[200:203], v111
	ds_read_b128 v[204:207], v111 offset:4096
	ds_read_b128 v[208:211], v115 offset:16384
	ds_read_b128 v[212:215], v115 offset:20480
	ds_read_b128 v[216:219], v112
	ds_read_b128 v[220:223], v112 offset:4096
	ds_read_b128 v[224:227], v116 offset:16384
	ds_read_b128 v[228:231], v116 offset:20480
	ds_read_b128 v[232:235], v113
	ds_read_b128 v[236:239], v113 offset:4096
	ds_read_b128 v[240:243], v117 offset:16384
	ds_read_b128 v[244:247], v117 offset:20480
	s_waitcnt lgkmcnt(0)
	s_barrier
	s_mov_b32 m0, s86
	v_lshl_add_u64 v[90:91], v[130:131], 0, v[90:91]
	global_load_lds_dwordx4 v[90:91], off
	s_add_u32 m0, s86, 0x4000
	v_lshl_add_u64 v[92:93], v[130:131], 0, v[92:93]
	global_load_lds_dwordx4 v[92:93], off
	s_add_u32 m0, s86, 0x1000
	v_lshl_add_u64 v[94:95], v[130:131], 0, v[94:95]
	global_load_lds_dwordx4 v[94:95], off
	s_add_u32 m0, s86, 0x5000
	v_lshl_add_u64 v[96:97], v[130:131], 0, v[96:97]
	global_load_lds_dwordx4 v[96:97], off
	s_add_u32 m0, s86, 0x2000
	v_lshl_add_u64 v[102:103], v[130:131], 0, v[102:103]
	global_load_lds_dwordx4 v[102:103], off
	s_add_u32 m0, s86, 0x6000
	v_lshl_add_u64 v[104:105], v[130:131], 0, v[104:105]
	global_load_lds_dwordx4 v[104:105], off
	s_add_u32 m0, s86, 0x3000
	v_lshl_add_u64 v[106:107], v[130:131], 0, v[106:107]
	global_load_lds_dwordx4 v[106:107], off
	s_add_u32 m0, s86, 0x7000
	v_lshl_add_u64 v[108:109], v[130:131], 0, v[108:109]
	global_load_lds_dwordx4 v[108:109], off
	v_mfma_f32_32x32x16_bf16 v[48:63], v[192:195], v[184:187], v[48:63]
	v_mfma_f32_32x32x16_bf16 v[32:47], v[192:195], v[188:191], v[32:47]
	v_mfma_f32_32x32x16_bf16 v[16:31], v[196:199], v[184:187], v[16:31]
	v_mfma_f32_32x32x16_bf16 v[0:15], v[196:199], v[188:191], v[0:15]
	v_mfma_f32_32x32x16_bf16 v[48:63], v[208:211], v[200:203], v[48:63]
	v_mfma_f32_32x32x16_bf16 v[32:47], v[208:211], v[204:207], v[32:47]
	v_mfma_f32_32x32x16_bf16 v[16:31], v[212:215], v[200:203], v[16:31]
	v_mfma_f32_32x32x16_bf16 v[0:15], v[212:215], v[204:207], v[0:15]
	v_mfma_f32_32x32x16_bf16 v[48:63], v[224:227], v[216:219], v[48:63]
	v_mfma_f32_32x32x16_bf16 v[32:47], v[224:227], v[220:223], v[32:47]
	v_mfma_f32_32x32x16_bf16 v[16:31], v[228:231], v[216:219], v[16:31]
	v_mfma_f32_32x32x16_bf16 v[0:15], v[228:231], v[220:223], v[0:15]
	v_mfma_f32_32x32x16_bf16 v[48:63], v[240:243], v[232:235], v[48:63]
	v_mfma_f32_32x32x16_bf16 v[32:47], v[240:243], v[236:239], v[32:47]
	v_mfma_f32_32x32x16_bf16 v[16:31], v[244:247], v[232:235], v[16:31]
	v_mfma_f32_32x32x16_bf16 v[0:15], v[244:247], v[236:239], v[0:15]
	s_waitcnt vmcnt(8)
	s_barrier
	ds_read_b128 v[184:187], v110 offset:32768
	ds_read_b128 v[188:191], v110 offset:36864
	ds_read_b128 v[192:195], v114 offset:49152
	ds_read_b128 v[196:199], v114 offset:53248
	ds_read_b128 v[200:203], v111 offset:32768
	ds_read_b128 v[204:207], v111 offset:36864
	ds_read_b128 v[208:211], v115 offset:49152
	ds_read_b128 v[212:215], v115 offset:53248
	ds_read_b128 v[216:219], v112 offset:32768
	ds_read_b128 v[220:223], v112 offset:36864
	ds_read_b128 v[224:227], v116 offset:49152
	ds_read_b128 v[228:231], v116 offset:53248
	ds_read_b128 v[232:235], v113 offset:32768
	ds_read_b128 v[236:239], v113 offset:36864
	ds_read_b128 v[240:243], v117 offset:49152
	ds_read_b128 v[244:247], v117 offset:53248
	s_waitcnt lgkmcnt(0)
	s_barrier
	s_add_u32 m0, s86, 0x8000
	v_lshl_add_u64 v[90:91], v[130:131], 0, v[90:91]
	global_load_lds_dwordx4 v[90:91], off
	s_add_u32 m0, s86, 0xc000
	v_lshl_add_u64 v[92:93], v[130:131], 0, v[92:93]
	global_load_lds_dwordx4 v[92:93], off
	s_add_u32 m0, s86, 0x9000
	v_lshl_add_u64 v[94:95], v[130:131], 0, v[94:95]
	global_load_lds_dwordx4 v[94:95], off
	s_add_u32 m0, s86, 0xd000
	v_lshl_add_u64 v[96:97], v[130:131], 0, v[96:97]
	global_load_lds_dwordx4 v[96:97], off
	s_add_u32 m0, s86, 0xa000
	v_lshl_add_u64 v[102:103], v[130:131], 0, v[102:103]
	global_load_lds_dwordx4 v[102:103], off
	s_add_u32 m0, s86, 0xe000
	v_lshl_add_u64 v[104:105], v[130:131], 0, v[104:105]
	global_load_lds_dwordx4 v[104:105], off
	s_add_u32 m0, s86, 0xb000
	v_lshl_add_u64 v[106:107], v[130:131], 0, v[106:107]
	global_load_lds_dwordx4 v[106:107], off
	s_add_u32 m0, s86, 0xf000
	v_lshl_add_u64 v[108:109], v[130:131], 0, v[108:109]
	global_load_lds_dwordx4 v[108:109], off
	v_mfma_f32_32x32x16_bf16 v[48:63], v[192:195], v[184:187], v[48:63]
	v_mfma_f32_32x32x16_bf16 v[32:47], v[192:195], v[188:191], v[32:47]
	v_mfma_f32_32x32x16_bf16 v[16:31], v[196:199], v[184:187], v[16:31]
	v_mfma_f32_32x32x16_bf16 v[0:15], v[196:199], v[188:191], v[0:15]
	v_mfma_f32_32x32x16_bf16 v[48:63], v[208:211], v[200:203], v[48:63]
	v_mfma_f32_32x32x16_bf16 v[32:47], v[208:211], v[204:207], v[32:47]
	v_mfma_f32_32x32x16_bf16 v[16:31], v[212:215], v[200:203], v[16:31]
	v_mfma_f32_32x32x16_bf16 v[0:15], v[212:215], v[204:207], v[0:15]
	v_mfma_f32_32x32x16_bf16 v[48:63], v[224:227], v[216:219], v[48:63]
	v_mfma_f32_32x32x16_bf16 v[32:47], v[224:227], v[220:223], v[32:47]
	v_mfma_f32_32x32x16_bf16 v[16:31], v[228:231], v[216:219], v[16:31]
	v_mfma_f32_32x32x16_bf16 v[0:15], v[228:231], v[220:223], v[0:15]
	v_mfma_f32_32x32x16_bf16 v[48:63], v[240:243], v[232:235], v[48:63]
	v_mfma_f32_32x32x16_bf16 v[32:47], v[240:243], v[236:239], v[32:47]
	v_mfma_f32_32x32x16_bf16 v[16:31], v[244:247], v[232:235], v[16:31]
	v_mfma_f32_32x32x16_bf16 v[0:15], v[244:247], v[236:239], v[0:15]
	s_waitcnt vmcnt(8)
	s_barrier
; DI int crow(int r, int h) { return (r & 3) + 8 * (r >> 2) + 4 * h; }
; #define D_COMPUTE(BUF) { D_MMA1(BUF, 0) D_MMA1(BUF, 1) D_MMA1(BUF, 2) D_MMA1(BUF, 3) }
; template <bool RESCALE, bool SWAP>
; DI void gemm_mainloop_glds(const bf16_t* __restrict__ A, const bf16_t* __restrict__ Bt, int m0, int n0, char* lds,
;                            f32x16 (&acc)[2][2], const float* ratio_lds) {
;     ...
;   for (int kt = 0; kt < NK; kt += 2) {
;     D_ISSUE(1, kt + 1);
;     if (RESCALE) {
;       if (kt == NK / 2) {
;         if (SWAP) {
;           const float sc0_ = ratio_lds[64 * wm + l31], sc1_ = ratio_lds[64 * wm + 32 + l31];
; #pragma unroll
;           for (int r = 0; r < 16; ++r) { c00[r] *= sc0_; c10[r] *= sc0_; c01[r] *= sc1_; c11[r] *= sc1_; }
;         } else {
; #pragma unroll
;           for (int r = 0; r < 16; ++r) {
;             float sc0_ = ratio_lds[64 * wm + crow(r, h)], sc1_ = ratio_lds[64 * wm + 32 + crow(r, h)];
;             c00[r] *= sc0_; c01[r] *= sc0_; c10[r] *= sc1_; c11[r] *= sc1_;
;           }
;         }
;       }
;     }
;     D_COMPUTE(0);
;     __syncthreads();
;     if (kt + 2 < NK) D_ISSUE(0, kt + 2);
;     D_COMPUTE(1);
;     __syncthreads();
;   }
;   acc[0][0] = c00; acc[0][1] = c01; acc[1][0] = c10; acc[1][1] = c11;
	s_add_i32 s77, s77, 2
	s_cmp_lt_u32 s77, 14
	s_cbranch_scc1 .Lgm_g1s_loop
	ds_read_b128 v[184:187], v110
	ds_read_b128 v[188:191], v110 offset:4096
	ds_read_b128 v[192:195], v114 offset:16384
	ds_read_b128 v[196:199], v114 offset:20480
	ds_read_b128 v[200:203], v111
	ds_read_b128 v[204:207], v111 offset:4096
	ds_read_b128 v[208:211], v115 offset:16384
	ds_read_b128 v[212:215], v115 offset:20480
	ds_read_b128 v[216:219], v112
	ds_read_b128 v[220:223], v112 offset:4096
	ds_read_b128 v[224:227], v116 offset:16384
	ds_read_b128 v[228:231], v116 offset:20480
	ds_read_b128 v[232:235], v113
	ds_read_b128 v[236:239], v113 offset:4096
	ds_read_b128 v[240:243], v117 offset:16384
	ds_read_b128 v[244:247], v117 offset:20480
	s_waitcnt lgkmcnt(0)
	v_mfma_f32_32x32x16_bf16 v[48:63], v[192:195], v[184:187], v[48:63]
	v_mfma_f32_32x32x16_bf16 v[32:47], v[192:195], v[188:191], v[32:47]
	v_mfma_f32_32x32x16_bf16 v[16:31], v[196:199], v[184:187], v[16:31]
	v_mfma_f32_32x32x16_bf16 v[0:15], v[196:199], v[188:191], v[0:15]
	v_mfma_f32_32x32x16_bf16 v[48:63], v[208:211], v[200:203], v[48:63]
	v_mfma_f32_32x32x16_bf16 v[32:47], v[208:211], v[204:207], v[32:47]
	v_mfma_f32_32x32x16_bf16 v[16:31], v[212:215], v[200:203], v[16:31]
	v_mfma_f32_32x32x16_bf16 v[0:15], v[212:215], v[204:207], v[0:15]
	v_mfma_f32_32x32x16_bf16 v[48:63], v[224:227], v[216:219], v[48:63]
	v_mfma_f32_32x32x16_bf16 v[32:47], v[224:227], v[220:223], v[32:47]
	v_mfma_f32_32x32x16_bf16 v[16:31], v[228:231], v[216:219], v[16:31]
	v_mfma_f32_32x32x16_bf16 v[0:15], v[228:231], v[220:223], v[0:15]
	v_mfma_f32_32x32x16_bf16 v[48:63], v[240:243], v[232:235], v[48:63]
	v_mfma_f32_32x32x16_bf16 v[32:47], v[240:243], v[236:239], v[32:47]
	v_mfma_f32_32x32x16_bf16 v[16:31], v[244:247], v[232:235], v[16:31]
	v_mfma_f32_32x32x16_bf16 v[0:15], v[244:247], v[236:239], v[0:15]
	s_waitcnt vmcnt(0)
	s_barrier
	ds_read_b128 v[184:187], v110 offset:32768
	ds_read_b128 v[188:191], v110 offset:36864
	ds_read_b128 v[192:195], v114 offset:49152
	ds_read_b128 v[196:199], v114 offset:53248
	ds_read_b128 v[200:203], v111 offset:32768
	ds_read_b128 v[204:207], v111 offset:36864
	ds_read_b128 v[208:211], v115 offset:49152
	ds_read_b128 v[212:215], v115 offset:53248
	ds_read_b128 v[216:219], v112 offset:32768
	ds_read_b128 v[220:223], v112 offset:36864
	ds_read_b128 v[224:227], v116 offset:49152
	ds_read_b128 v[228:231], v116 offset:53248
	ds_read_b128 v[232:235], v113 offset:32768
	ds_read_b128 v[236:239], v113 offset:36864
	ds_read_b128 v[240:243], v117 offset:49152
	ds_read_b128 v[244:247], v117 offset:53248
	s_waitcnt lgkmcnt(0)
	s_barrier
	v_mfma_f32_32x32x16_bf16 v[48:63], v[192:195], v[184:187], v[48:63]
	v_mfma_f32_32x32x16_bf16 v[32:47], v[192:195], v[188:191], v[32:47]
	v_mfma_f32_32x32x16_bf16 v[16:31], v[196:199], v[184:187], v[16:31]
	v_mfma_f32_32x32x16_bf16 v[0:15], v[196:199], v[188:191], v[0:15]
	v_mfma_f32_32x32x16_bf16 v[48:63], v[208:211], v[200:203], v[48:63]
	v_mfma_f32_32x32x16_bf16 v[32:47], v[208:211], v[204:207], v[32:47]
	v_mfma_f32_32x32x16_bf16 v[16:31], v[212:215], v[200:203], v[16:31]
	v_mfma_f32_32x32x16_bf16 v[0:15], v[212:215], v[204:207], v[0:15]
	v_mfma_f32_32x32x16_bf16 v[48:63], v[224:227], v[216:219], v[48:63]
	v_mfma_f32_32x32x16_bf16 v[32:47], v[224:227], v[220:223], v[32:47]
	v_mfma_f32_32x32x16_bf16 v[16:31], v[228:231], v[216:219], v[16:31]
	v_mfma_f32_32x32x16_bf16 v[0:15], v[228:231], v[220:223], v[0:15]
	v_mfma_f32_32x32x16_bf16 v[48:63], v[240:243], v[232:235], v[48:63]
	v_mfma_f32_32x32x16_bf16 v[32:47], v[240:243], v[236:239], v[32:47]
	v_mfma_f32_32x32x16_bf16 v[16:31], v[244:247], v[232:235], v[16:31]
	v_mfma_f32_32x32x16_bf16 v[0:15], v[244:247], v[236:239], v[0:15]
	s_nop 7
	s_nop 7
	s_setprio 0

; DI int otid() { int t; asm volatile("v_mov_b32 %0, %1" : "=v"(t) : "v"((int)threadIdx.x)); return t; }
; template <bool RESCALE, bool SWAP>
; DI void gemm_mainloop_glds(const bf16_t* __restrict__ A, const bf16_t* __restrict__ Bt, int m0, int n0, char* lds,
;                            f32x16 (&acc)[2][2], const float* ratio_lds) {
;   constexpr int K = 1024, NK = K / 64, OPB = 16384, STB = 2 * OPB;
;   const int tid = otid(), lane = tid & 63, w = tid >> 6, wm = w >> 1, wn = w & 1, l31 = lane & 31, h = lane >> 5;
;   const int lr = lane >> 3, csrc = (lane & 7) ^ (4 * (w & 1) + (lr >> 1));
;   const bf16_t* ag = A + (size_t)(m0 + 8 * w + lr) * K + csrc * 8;
;   const bf16_t* bg = Bt + (size_t)(n0 + 8 * w + lr) * K + csrc * 8;
;   const unsigned lbase = (unsigned)(size_t)lds + (unsigned)w * 1024u;
;   const int swz = (l31 >> 1) & 7;
;   const char* fa = lds + (64 * wm + l31) * 128;
;   const char* fb = lds + OPB + (64 * wn + l31) * 128;
;   int fo[4];
; #pragma unroll
;   for (int s_ = 0; s_ < 4; ++s_) fo[s_] = ((2 * s_ + h) ^ swz) * 16;
;   f32x16 c00, c01, c10, c11;
; #pragma unroll
;   for (int r = 0; r < 16; ++r) { c00[r] = 0.f; c01[r] = 0.f; c10[r] = 0.f; c11[r] = 0.f; }
;     ...
;   D_ISSUE(0, 0);
;   __syncthreads();
; #pragma unroll 1
;   for (int kt = 0; kt < NK; kt += 2) {
;     D_ISSUE(1, kt + 1);
.LBB0_185:
	s_and_b64 vcc, exec, s[78:79]
	s_cbranch_vccz .LBB0_169
	s_setprio 1
	v_readlane_b32 s78, v182, 19
	v_readlane_b32 s79, v182, 20
	v_lshrrev_b32_e32 v119, 3, v118
	v_lshrrev_b32_e32 v120, 6, v118
	v_and_b32_e32 v121, 1, v120
	v_bfe_u32 v122, v118, 4, 2
	v_lshl_or_b32 v122, v121, 2, v122
	v_and_b32_e32 v123, 7, v118
	v_xor_b32_e32 v122, v122, v123
	v_lshlrev_b32_e32 v124, 10, v120
	v_add_u32_e32 v126, s84, v119
	v_add_u32_e32 v128, s76, v119
	v_readfirstlane_b32 s86, v124
	v_lshlrev_b32_e32 v126, 11, v126
	v_lshlrev_b32_e32 v128, 11, v128
	v_lshl_or_b32 v126, v122, 4, v126
	v_lshl_or_b32 v128, v122, 4, v128
	v_mov_b32_e32 v127, 0
	v_mov_b32_e32 v129, 0
	v_lshl_add_u64 v[90:91], v[126:127], 0, s[78:79]
	v_lshl_add_u64 v[92:93], v[128:129], 0, s[20:21]
	v_lshl_add_u64 v[94:95], v[90:91], 0, s[34:35]
	v_lshl_add_u64 v[102:103], v[90:91], 0, s[40:41]
	v_lshl_add_u64 v[106:107], v[90:91], 0, s[42:43]
	v_lshl_add_u64 v[96:97], v[92:93], 0, s[34:35]
	v_lshl_add_u64 v[104:105], v[92:93], 0, s[40:41]
	v_lshl_add_u64 v[108:109], v[92:93], 0, s[42:43]
	v_mov_b32_e32 v130, 0x80
	v_mov_b32_e32 v131, 0
	s_mov_b32 m0, s86
	s_nop 0
	global_load_lds_dwordx4 v[90:91], off
	s_add_u32 m0, s86, 0x4000
	s_nop 0
	global_load_lds_dwordx4 v[92:93], off
	s_add_u32 m0, s86, 0x1000
	s_nop 0
	global_load_lds_dwordx4 v[94:95], off
	s_add_u32 m0, s86, 0x5000
	s_nop 0
	global_load_lds_dwordx4 v[96:97], off
	s_add_u32 m0, s86, 0x2000
	s_nop 0
	global_load_lds_dwordx4 v[102:103], off
	s_add_u32 m0, s86, 0x6000
	s_nop 0
	global_load_lds_dwordx4 v[104:105], off
	s_add_u32 m0, s86, 0x3000
	s_nop 0
	global_load_lds_dwordx4 v[106:107], off
	s_add_u32 m0, s86, 0x7000
	s_nop 0
	global_load_lds_dwordx4 v[108:109], off
	s_add_u32 m0, s86, 0x8000
	v_lshl_add_u64 v[90:91], v[130:131], 0, v[90:91]
	global_load_lds_dwordx4 v[90:91], off
	s_add_u32 m0, s86, 0xc000
	v_lshl_add_u64 v[92:93], v[130:131], 0, v[92:93]
	global_load_lds_dwordx4 v[92:93], off
	s_add_u32 m0, s86, 0x9000
	v_lshl_add_u64 v[94:95], v[130:131], 0, v[94:95]
	global_load_lds_dwordx4 v[94:95], off
	s_add_u32 m0, s86, 0xd000
	v_lshl_add_u64 v[96:97], v[130:131], 0, v[96:97]
	global_load_lds_dwordx4 v[96:97], off
	s_add_u32 m0, s86, 0xa000
	v_lshl_add_u64 v[102:103], v[130:131], 0, v[102:103]
	global_load_lds_dwordx4 v[102:103], off
	s_add_u32 m0, s86, 0xe000
	v_lshl_add_u64 v[104:105], v[130:131], 0, v[104:105]
	global_load_lds_dwordx4 v[104:105], off
	s_add_u32 m0, s86, 0xb000
	v_lshl_add_u64 v[106:107], v[130:131], 0, v[106:107]
	global_load_lds_dwordx4 v[106:107], off
	s_add_u32 m0, s86, 0xf000
	v_lshl_add_u64 v[108:109], v[130:131], 0, v[108:109]
	global_load_lds_dwordx4 v[108:109], off
	v_and_b32_e32 v119, 31, v118
	v_bfe_u32 v120, v118, 5, 1
	v_bfe_u32 v121, v118, 1, 3
	v_lshrrev_b32_e32 v122, 7, v118
	v_bfe_u32 v123, v118, 6, 1
	v_lshl_or_b32 v122, v122, 6, v119
	v_lshl_or_b32 v123, v123, 6, v119
	v_lshlrev_b32_e32 v122, 7, v122
	v_lshlrev_b32_e32 v123, 7, v123
	v_or_b32_e32 v124, 0, v120
	v_xor_b32_e32 v124, v124, v121
	v_lshl_add_u32 v110, v124, 4, v122
	v_lshl_add_u32 v114, v124, 4, v123
	v_or_b32_e32 v124, 2, v120
	v_xor_b32_e32 v124, v124, v121
	v_lshl_add_u32 v111, v124, 4, v122
	v_lshl_add_u32 v115, v124, 4, v123
	v_or_b32_e32 v124, 4, v120
	v_xor_b32_e32 v124, v124, v121
	v_lshl_add_u32 v112, v124, 4, v122
	v_lshl_add_u32 v116, v124, 4, v123
	v_or_b32_e32 v124, 6, v120
	v_xor_b32_e32 v124, v124, v121
	v_lshl_add_u32 v113, v124, 4, v122
	v_lshl_add_u32 v117, v124, 4, v123
	v_mov_b32_e32 v32, 0
	v_mov_b32_e32 v33, 0
	v_mov_b32_e32 v34, 0
	v_mov_b32_e32 v35, 0
	v_mov_b32_e32 v36, 0
	v_mov_b32_e32 v37, 0
	v_mov_b32_e32 v38, 0
	v_mov_b32_e32 v39, 0
	v_mov_b32_e32 v40, 0
	v_mov_b32_e32 v41, 0
	v_mov_b32_e32 v42, 0
	v_mov_b32_e32 v43, 0
	v_mov_b32_e32 v44, 0
	v_mov_b32_e32 v45, 0
	v_mov_b32_e32 v46, 0
	v_mov_b32_e32 v47, 0
	v_mov_b32_e32 v0, 0
	v_mov_b32_e32 v1, 0
	v_mov_b32_e32 v2, 0
	v_mov_b32_e32 v3, 0
	v_mov_b32_e32 v4, 0
	v_mov_b32_e32 v5, 0
	v_mov_b32_e32 v6, 0
	v_mov_b32_e32 v7, 0
	v_mov_b32_e32 v8, 0
	v_mov_b32_e32 v9, 0
	v_mov_b32_e32 v10, 0
	v_mov_b32_e32 v11, 0
	v_mov_b32_e32 v12, 0
	v_mov_b32_e32 v13, 0
	v_mov_b32_e32 v14, 0
	v_mov_b32_e32 v15, 0
	v_mov_b32_e32 v48, 0
	v_mov_b32_e32 v49, 0
	v_mov_b32_e32 v50, 0
	v_mov_b32_e32 v51, 0
	v_mov_b32_e32 v52, 0
	v_mov_b32_e32 v53, 0
	v_mov_b32_e32 v54, 0
	v_mov_b32_e32 v55, 0
	v_mov_b32_e32 v56, 0
	v_mov_b32_e32 v57, 0
	v_mov_b32_e32 v58, 0
	v_mov_b32_e32 v59, 0
	v_mov_b32_e32 v60, 0
	v_mov_b32_e32 v61, 0
	v_mov_b32_e32 v62, 0
	v_mov_b32_e32 v63, 0
	v_mov_b32_e32 v16, 0
	v_mov_b32_e32 v17, 0
	v_mov_b32_e32 v18, 0
	v_mov_b32_e32 v19, 0
	v_mov_b32_e32 v20, 0
	v_mov_b32_e32 v21, 0
	v_mov_b32_e32 v22, 0
	v_mov_b32_e32 v23, 0
	v_mov_b32_e32 v24, 0
	v_mov_b32_e32 v25, 0
	v_mov_b32_e32 v26, 0
	v_mov_b32_e32 v27, 0
	v_mov_b32_e32 v28, 0
	v_mov_b32_e32 v29, 0
	v_mov_b32_e32 v30, 0
	v_mov_b32_e32 v31, 0
	s_mov_b32 s77, 0
	s_waitcnt vmcnt(8)
	s_barrier
; DI int crow(int r, int h) { return (r & 3) + 8 * (r >> 2) + 4 * h; }
; #define D_COMPUTE(BUF) { D_MMA1(BUF, 0) D_MMA1(BUF, 1) D_MMA1(BUF, 2) D_MMA1(BUF, 3) }
; template <bool RESCALE, bool SWAP>
; DI void gemm_mainloop_glds(const bf16_t* __restrict__ A, const bf16_t* __restrict__ Bt, int m0, int n0, char* lds,
;                            f32x16 (&acc)[2][2], const float* ratio_lds) {
;     ...
;   for (int kt = 0; kt < NK; kt += 2) {
;     D_ISSUE(1, kt + 1);
;     if (RESCALE) {
;       if (kt == NK / 2) {
;         if (SWAP) {
;           const float sc0_ = ratio_lds[64 * wm + l31], sc1_ = ratio_lds[64 * wm + 32 + l31];
; #pragma unroll
;           for (int r = 0; r < 16; ++r) { c00[r] *= sc0_; c10[r] *= sc0_; c01[r] *= sc1_; c11[r] *= sc1_; }
;         } else {
; #pragma unroll
;           for (int r = 0; r < 16; ++r) {
;             float sc0_ = ratio_lds[64 * wm + crow(r, h)], sc1_ = ratio_lds[64 * wm + 32 + crow(r, h)];
;             c00[r] *= sc0_; c01[r] *= sc0_; c10[r] *= sc1_; c11[r] *= sc1_;
;           }
;         }
;       }
;     }
;     D_COMPUTE(0);
;     __syncthreads();
;     if (kt + 2 < NK) D_ISSUE(0, kt + 2);
;     D_COMPUTE(1);
;     __syncthreads();
;   }
.Lgm_g1n_loop:
	ds_read_b128 v[184:187], v110
	ds_read_b128 v[188:191], v110 offset:4096
	ds_read_b128 v[192:195], v114 offset:16384
	ds_read_b128 v[196:199], v114 offset:20480
	ds_read_b128 v[200:203], v111
	ds_read_b128 v[204:207], v111 offset:4096
	ds_read_b128 v[208:211], v115 offset:16384
	ds_read_b128 v[212:215], v115 offset:20480
	ds_read_b128 v[216:219], v112
	ds_read_b128 v[220:223], v112 offset:4096
	ds_read_b128 v[224:227], v116 offset:16384
	ds_read_b128 v[228:231], v116 offset:20480
	ds_read_b128 v[232:235], v113
	ds_read_b128 v[236:239], v113 offset:4096
	ds_read_b128 v[240:243], v117 offset:16384
	ds_read_b128 v[244:247], v117 offset:20480
	s_waitcnt lgkmcnt(0)
	s_barrier
	s_mov_b32 m0, s86
	v_lshl_add_u64 v[90:91], v[130:131], 0, v[90:91]
	global_load_lds_dwordx4 v[90:91], off
	s_add_u32 m0, s86, 0x4000
	v_lshl_add_u64 v[92:93], v[130:131], 0, v[92:93]
	global_load_lds_dwordx4 v[92:93], off
	s_add_u32 m0, s86, 0x1000
	v_lshl_add_u64 v[94:95], v[130:131], 0, v[94:95]
	global_load_lds_dwordx4 v[94:95], off
	s_add_u32 m0, s86, 0x5000
	v_lshl_add_u64 v[96:97], v[130:131], 0, v[96:97]
	global_load_lds_dwordx4 v[96:97], off
	s_add_u32 m0, s86, 0x2000
	v_lshl_add_u64 v[102:103], v[130:131], 0, v[102:103]
	global_load_lds_dwordx4 v[102:103], off
	s_add_u32 m0, s86, 0x6000
	v_lshl_add_u64 v[104:105], v[130:131], 0, v[104:105]
	global_load_lds_dwordx4 v[104:105], off
	s_add_u32 m0, s86, 0x3000
	v_lshl_add_u64 v[106:107], v[130:131], 0, v[106:107]
	global_load_lds_dwordx4 v[106:107], off
	s_add_u32 m0, s86, 0x7000
	v_lshl_add_u64 v[108:109], v[130:131], 0, v[108:109]
	global_load_lds_dwordx4 v[108:109], off
	v_mfma_f32_32x32x16_bf16 v[32:47], v[184:187], v[192:195], v[32:47]
	v_mfma_f32_32x32x16_bf16 v[0:15], v[184:187], v[196:199], v[0:15]
	v_mfma_f32_32x32x16_bf16 v[48:63], v[188:191], v[192:195], v[48:63]
	v_mfma_f32_32x32x16_bf16 v[16:31], v[188:191], v[196:199], v[16:31]
	v_mfma_f32_32x32x16_bf16 v[32:47], v[200:203], v[208:211], v[32:47]
	v_mfma_f32_32x32x16_bf16 v[0:15], v[200:203], v[212:215], v[0:15]
	v_mfma_f32_32x32x16_bf16 v[48:63], v[204:207], v[208:211], v[48:63]
	v_mfma_f32_32x32x16_bf16 v[16:31], v[204:207], v[212:215], v[16:31]
	v_mfma_f32_32x32x16_bf16 v[32:47], v[216:219], v[224:227], v[32:47]
	v_mfma_f32_32x32x16_bf16 v[0:15], v[216:219], v[228:231], v[0:15]
	v_mfma_f32_32x32x16_bf16 v[48:63], v[220:223], v[224:227], v[48:63]
	v_mfma_f32_32x32x16_bf16 v[16:31], v[220:223], v[228:231], v[16:31]
	v_mfma_f32_32x32x16_bf16 v[32:47], v[232:235], v[240:243], v[32:47]
	v_mfma_f32_32x32x16_bf16 v[0:15], v[232:235], v[244:247], v[0:15]
	v_mfma_f32_32x32x16_bf16 v[48:63], v[236:239], v[240:243], v[48:63]
	v_mfma_f32_32x32x16_bf16 v[16:31], v[236:239], v[244:247], v[16:31]
	s_waitcnt vmcnt(8)
	s_barrier
	ds_read_b128 v[184:187], v110 offset:32768
	ds_read_b128 v[188:191], v110 offset:36864
	ds_read_b128 v[192:195], v114 offset:49152
	ds_read_b128 v[196:199], v114 offset:53248
	ds_read_b128 v[200:203], v111 offset:32768
	ds_read_b128 v[204:207], v111 offset:36864
	ds_read_b128 v[208:211], v115 offset:49152
	ds_read_b128 v[212:215], v115 offset:53248
	ds_read_b128 v[216:219], v112 offset:32768
	ds_read_b128 v[220:223], v112 offset:36864
	ds_read_b128 v[224:227], v116 offset:49152
	ds_read_b128 v[228:231], v116 offset:53248
	ds_read_b128 v[232:235], v113 offset:32768
	ds_read_b128 v[236:239], v113 offset:36864
	ds_read_b128 v[240:243], v117 offset:49152
	ds_read_b128 v[244:247], v117 offset:53248
	s_waitcnt lgkmcnt(0)
	s_barrier
	s_add_u32 m0, s86, 0x8000
	v_lshl_add_u64 v[90:91], v[130:131], 0, v[90:91]
	global_load_lds_dwordx4 v[90:91], off
	s_add_u32 m0, s86, 0xc000
	v_lshl_add_u64 v[92:93], v[130:131], 0, v[92:93]
	global_load_lds_dwordx4 v[92:93], off
	s_add_u32 m0, s86, 0x9000
	v_lshl_add_u64 v[94:95], v[130:131], 0, v[94:95]
	global_load_lds_dwordx4 v[94:95], off
	s_add_u32 m0, s86, 0xd000
	v_lshl_add_u64 v[96:97], v[130:131], 0, v[96:97]
	global_load_lds_dwordx4 v[96:97], off
	s_add_u32 m0, s86, 0xa000
	v_lshl_add_u64 v[102:103], v[130:131], 0, v[102:103]
	global_load_lds_dwordx4 v[102:103], off
	s_add_u32 m0, s86, 0xe000
	v_lshl_add_u64 v[104:105], v[130:131], 0, v[104:105]
	global_load_lds_dwordx4 v[104:105], off
	s_add_u32 m0, s86, 0xb000
	v_lshl_add_u64 v[106:107], v[130:131], 0, v[106:107]
	global_load_lds_dwordx4 v[106:107], off
	s_add_u32 m0, s86, 0xf000
	v_lshl_add_u64 v[108:109], v[130:131], 0, v[108:109]
	global_load_lds_dwordx4 v[108:109], off
	v_mfma_f32_32x32x16_bf16 v[32:47], v[184:187], v[192:195], v[32:47]
	v_mfma_f32_32x32x16_bf16 v[0:15], v[184:187], v[196:199], v[0:15]
	v_mfma_f32_32x32x16_bf16 v[48:63], v[188:191], v[192:195], v[48:63]
	v_mfma_f32_32x32x16_bf16 v[16:31], v[188:191], v[196:199], v[16:31]
	v_mfma_f32_32x32x16_bf16 v[32:47], v[200:203], v[208:211], v[32:47]
	v_mfma_f32_32x32x16_bf16 v[0:15], v[200:203], v[212:215], v[0:15]
	v_mfma_f32_32x32x16_bf16 v[48:63], v[204:207], v[208:211], v[48:63]
	v_mfma_f32_32x32x16_bf16 v[16:31], v[204:207], v[212:215], v[16:31]
	v_mfma_f32_32x32x16_bf16 v[32:47], v[216:219], v[224:227], v[32:47]
	v_mfma_f32_32x32x16_bf16 v[0:15], v[216:219], v[228:231], v[0:15]
	v_mfma_f32_32x32x16_bf16 v[48:63], v[220:223], v[224:227], v[48:63]
	v_mfma_f32_32x32x16_bf16 v[16:31], v[220:223], v[228:231], v[16:31]
	v_mfma_f32_32x32x16_bf16 v[32:47], v[232:235], v[240:243], v[32:47]
	v_mfma_f32_32x32x16_bf16 v[0:15], v[232:235], v[244:247], v[0:15]
	v_mfma_f32_32x32x16_bf16 v[48:63], v[236:239], v[240:243], v[48:63]
	v_mfma_f32_32x32x16_bf16 v[16:31], v[236:239], v[244:247], v[16:31]
	s_waitcnt vmcnt(8)
	s_barrier
; DI int crow(int r, int h) { return (r & 3) + 8 * (r >> 2) + 4 * h; }
; #define D_COMPUTE(BUF) { D_MMA1(BUF, 0) D_MMA1(BUF, 1) D_MMA1(BUF, 2) D_MMA1(BUF, 3) }
; template <bool RESCALE, bool SWAP>
; DI void gemm_mainloop_glds(const bf16_t* __restrict__ A, const bf16_t* __restrict__ Bt, int m0, int n0, char* lds,
;                            f32x16 (&acc)[2][2], const float* ratio_lds) {
;     ...
;   for (int kt = 0; kt < NK; kt += 2) {
;     D_ISSUE(1, kt + 1);
;     if (RESCALE) {
;       if (kt == NK / 2) {
;         if (SWAP) {
;           const float sc0_ = ratio_lds[64 * wm + l31], sc1_ = ratio_lds[64 * wm + 32 + l31];
; #pragma unroll
;           for (int r = 0; r < 16; ++r) { c00[r] *= sc0_; c10[r] *= sc0_; c01[r] *= sc1_; c11[r] *= sc1_; }
;         } else {
; #pragma unroll
;           for (int r = 0; r < 16; ++r) {
;             float sc0_ = ratio_lds[64 * wm + crow(r, h)], sc1_ = ratio_lds[64 * wm + 32 + crow(r, h)];
;             c00[r] *= sc0_; c01[r] *= sc0_; c10[r] *= sc1_; c11[r] *= sc1_;
;           }
;         }
;       }
;     }
;     D_COMPUTE(0);
;     __syncthreads();
;     if (kt + 2 < NK) D_ISSUE(0, kt + 2);
;     D_COMPUTE(1);
;     __syncthreads();
;   }
;   acc[0][0] = c00; acc[0][1] = c01; acc[1][0] = c10; acc[1][1] = c11;
	s_add_i32 s77, s77, 2
	s_cmp_lt_u32 s77, 14
	s_cbranch_scc1 .Lgm_g1n_loop
	ds_read_b128 v[184:187], v110
	ds_read_b128 v[188:191], v110 offset:4096
	ds_read_b128 v[192:195], v114 offset:16384
	ds_read_b128 v[196:199], v114 offset:20480
	ds_read_b128 v[200:203], v111
	ds_read_b128 v[204:207], v111 offset:4096
	ds_read_b128 v[208:211], v115 offset:16384
	ds_read_b128 v[212:215], v115 offset:20480
	ds_read_b128 v[216:219], v112
	ds_read_b128 v[220:223], v112 offset:4096
	ds_read_b128 v[224:227], v116 offset:16384
	ds_read_b128 v[228:231], v116 offset:20480
	ds_read_b128 v[232:235], v113
	ds_read_b128 v[236:239], v113 offset:4096
	ds_read_b128 v[240:243], v117 offset:16384
	ds_read_b128 v[244:247], v117 offset:20480
	s_waitcnt lgkmcnt(0)
	v_mfma_f32_32x32x16_bf16 v[32:47], v[184:187], v[192:195], v[32:47]
	v_mfma_f32_32x32x16_bf16 v[0:15], v[184:187], v[196:199], v[0:15]
	v_mfma_f32_32x32x16_bf16 v[48:63], v[188:191], v[192:195], v[48:63]
	v_mfma_f32_32x32x16_bf16 v[16:31], v[188:191], v[196:199], v[16:31]
	v_mfma_f32_32x32x16_bf16 v[32:47], v[200:203], v[208:211], v[32:47]
	v_mfma_f32_32x32x16_bf16 v[0:15], v[200:203], v[212:215], v[0:15]
	v_mfma_f32_32x32x16_bf16 v[48:63], v[204:207], v[208:211], v[48:63]
	v_mfma_f32_32x32x16_bf16 v[16:31], v[204:207], v[212:215], v[16:31]
	v_mfma_f32_32x32x16_bf16 v[32:47], v[216:219], v[224:227], v[32:47]
	v_mfma_f32_32x32x16_bf16 v[0:15], v[216:219], v[228:231], v[0:15]
	v_mfma_f32_32x32x16_bf16 v[48:63], v[220:223], v[224:227], v[48:63]
	v_mfma_f32_32x32x16_bf16 v[16:31], v[220:223], v[228:231], v[16:31]
	v_mfma_f32_32x32x16_bf16 v[32:47], v[232:235], v[240:243], v[32:47]
	v_mfma_f32_32x32x16_bf16 v[0:15], v[232:235], v[244:247], v[0:15]
	v_mfma_f32_32x32x16_bf16 v[48:63], v[236:239], v[240:243], v[48:63]
	v_mfma_f32_32x32x16_bf16 v[16:31], v[236:239], v[244:247], v[16:31]
	s_waitcnt vmcnt(0)
	s_barrier
	ds_read_b128 v[184:187], v110 offset:32768
	ds_read_b128 v[188:191], v110 offset:36864
	ds_read_b128 v[192:195], v114 offset:49152
	ds_read_b128 v[196:199], v114 offset:53248
	ds_read_b128 v[200:203], v111 offset:32768
	ds_read_b128 v[204:207], v111 offset:36864
	ds_read_b128 v[208:211], v115 offset:49152
	ds_read_b128 v[212:215], v115 offset:53248
	ds_read_b128 v[216:219], v112 offset:32768
	ds_read_b128 v[220:223], v112 offset:36864
	ds_read_b128 v[224:227], v116 offset:49152
	ds_read_b128 v[228:231], v116 offset:53248
	ds_read_b128 v[232:235], v113 offset:32768
	ds_read_b128 v[236:239], v113 offset:36864
	ds_read_b128 v[240:243], v117 offset:49152
	ds_read_b128 v[244:247], v117 offset:53248
	s_waitcnt lgkmcnt(0)
	s_barrier
	v_mfma_f32_32x32x16_bf16 v[32:47], v[184:187], v[192:195], v[32:47]
	v_mfma_f32_32x32x16_bf16 v[0:15], v[184:187], v[196:199], v[0:15]
	v_mfma_f32_32x32x16_bf16 v[48:63], v[188:191], v[192:195], v[48:63]
	v_mfma_f32_32x32x16_bf16 v[16:31], v[188:191], v[196:199], v[16:31]
	v_mfma_f32_32x32x16_bf16 v[32:47], v[200:203], v[208:211], v[32:47]
	v_mfma_f32_32x32x16_bf16 v[0:15], v[200:203], v[212:215], v[0:15]
	v_mfma_f32_32x32x16_bf16 v[48:63], v[204:207], v[208:211], v[48:63]
	v_mfma_f32_32x32x16_bf16 v[16:31], v[204:207], v[212:215], v[16:31]
	v_mfma_f32_32x32x16_bf16 v[32:47], v[216:219], v[224:227], v[32:47]
	v_mfma_f32_32x32x16_bf16 v[0:15], v[216:219], v[228:231], v[0:15]
	v_mfma_f32_32x32x16_bf16 v[48:63], v[220:223], v[224:227], v[48:63]
	v_mfma_f32_32x32x16_bf16 v[16:31], v[220:223], v[228:231], v[16:31]
	v_mfma_f32_32x32x16_bf16 v[32:47], v[232:235], v[240:243], v[32:47]
	v_mfma_f32_32x32x16_bf16 v[0:15], v[232:235], v[244:247], v[0:15]
	v_mfma_f32_32x32x16_bf16 v[48:63], v[236:239], v[240:243], v[48:63]
	v_mfma_f32_32x32x16_bf16 v[16:31], v[236:239], v[244:247], v[16:31]
	s_nop 7
	s_nop 7
	s_setprio 0
	s_branch .LBB0_168

; __device__ void phase_gemm_out(const Params& p, int bid, int nb, char* lds, const TileMap& tm) {
;     ...
;     float* stf = (float*)lds;
; #pragma unroll
;     for (int j = 0; j < 2; ++j)
; #pragma unroll
;       for (int i = 0; i < 2; ++i) {
;         const int rl = 64 * wm + 32 * i + l31;
;         const float rb = rbv[rl];
; #pragma unroll
;         for (int g = 0; g < 4; ++g) {
;           const f32x16& a = acc[j][i];
;           *(float4*)(stf + rl * 132 + 64 * wn + 32 * j + 8 * g + 4 * h) = make_float4(a[4 * g] * rb, a[4 * g + 1] * rb, a[4 * g + 2] * rb, a[4 * g + 3] * rb);
;         }
;       }
;     __syncthreads();
;     const int b = m0 >> 13;
;     const float* gate = ada + b * 6144 + 2048 + n0;
;     {
;       const int c32 = tid & 31, r0 = tid >> 5;
;       const float4 gt = *(const float4*)(gate + c32 * 4);
; #pragma unroll
;       for (int q = 0; q < 16; ++q) {
;         const int row = r0 + 8 * q;
;         const size_t idx = (size_t)(m0 + row) * 1024 + n0 + c32 * 4;
;         const float4 xv = *(const float4*)(p.x + idx);
;         const float4 mv = *(const float4*)(stf + row * 132 + c32 * 4);
;         *(float4*)(p.out + idx) = make_float4(ALPHA * xv.x + gt.x * mv.x, ALPHA * xv.y + gt.y * mv.y, ALPHA * xv.z + gt.z * mv.z, ALPHA * xv.w + gt.w * mv.w);
;       }
.LBB0_310:
	s_setprio 0
	ds_read_b32 v0, v80
	s_lshr_b32 s1, s44, 6
	s_mul_i32 s40, s1, 0x1800
	s_ashr_i32 s41, s40, 31
	s_lshl_b64 s[40:41], s[40:41], 2
	s_waitcnt lgkmcnt(0)
	v_pk_mul_f32 v[50:51], v[50:51], v[0:1] op_sel_hi:[1,0]
	v_pk_mul_f32 v[52:53], v[52:53], v[0:1] op_sel_hi:[1,0]
	v_pk_mul_f32 v[54:55], v[54:55], v[0:1] op_sel_hi:[1,0]
	v_pk_mul_f32 v[56:57], v[56:57], v[0:1] op_sel_hi:[1,0]
	ds_write_b128 v82, v[50:53]
	ds_write_b128 v82, v[54:57] offset:32
	v_pk_mul_f32 v[50:51], v[58:59], v[0:1] op_sel_hi:[1,0]
	v_pk_mul_f32 v[52:53], v[60:61], v[0:1] op_sel_hi:[1,0]
	ds_write_b128 v82, v[50:53] offset:64
	v_pk_mul_f32 v[50:51], v[62:63], v[0:1] op_sel_hi:[1,0]
	v_pk_mul_f32 v[52:53], v[64:65], v[0:1] op_sel_hi:[1,0]
	ds_write_b128 v82, v[50:53] offset:96
	ds_read_b32 v0, v81
	s_add_u32 s42, s92, s40
	s_addc_u32 s43, s93, s41
	s_ashr_i32 s1, s0, 31
	s_lshl_b64 s[40:41], s[0:1], 2
	s_waitcnt lgkmcnt(0)
	v_pk_mul_f32 v[34:35], v[34:35], v[0:1] op_sel_hi:[1,0]
	v_pk_mul_f32 v[36:37], v[36:37], v[0:1] op_sel_hi:[1,0]
	ds_write_b128 v82, v[34:37] offset:16896
	v_pk_mul_f32 v[34:35], v[38:39], v[0:1] op_sel_hi:[1,0]
	v_pk_mul_f32 v[36:37], v[40:41], v[0:1] op_sel_hi:[1,0]
	ds_write_b128 v82, v[34:37] offset:16928
	v_pk_mul_f32 v[34:35], v[42:43], v[0:1] op_sel_hi:[1,0]
	v_pk_mul_f32 v[36:37], v[44:45], v[0:1] op_sel_hi:[1,0]
	ds_write_b128 v82, v[34:37] offset:16960
	v_pk_mul_f32 v[34:35], v[46:47], v[0:1] op_sel_hi:[1,0]
	v_pk_mul_f32 v[36:37], v[48:49], v[0:1] op_sel_hi:[1,0]
	ds_write_b128 v82, v[34:37] offset:16992
	ds_read_b32 v0, v80
	s_add_u32 s40, s42, s40
	s_addc_u32 s41, s43, s41
	s_add_i32 s21, s21, 1
	s_waitcnt lgkmcnt(0)
	v_pk_mul_f32 v[18:19], v[18:19], v[0:1] op_sel_hi:[1,0]
	v_pk_mul_f32 v[20:21], v[20:21], v[0:1] op_sel_hi:[1,0]
	ds_write_b128 v82, v[18:21] offset:128
	v_pk_mul_f32 v[18:19], v[22:23], v[0:1] op_sel_hi:[1,0]
	v_pk_mul_f32 v[20:21], v[24:25], v[0:1] op_sel_hi:[1,0]
	ds_write_b128 v82, v[18:21] offset:160
	v_pk_mul_f32 v[18:19], v[26:27], v[0:1] op_sel_hi:[1,0]
	v_pk_mul_f32 v[20:21], v[28:29], v[0:1] op_sel_hi:[1,0]
	ds_write_b128 v82, v[18:21] offset:192
	v_pk_mul_f32 v[18:19], v[30:31], v[0:1] op_sel_hi:[1,0]
	v_pk_mul_f32 v[20:21], v[32:33], v[0:1] op_sel_hi:[1,0]
	ds_write_b128 v82, v[18:21] offset:224
	ds_read_b32 v0, v81
	s_waitcnt lgkmcnt(0)
	v_pk_mul_f32 v[2:3], v[2:3], v[0:1] op_sel_hi:[1,0]
	v_pk_mul_f32 v[4:5], v[4:5], v[0:1] op_sel_hi:[1,0]
	ds_write_b128 v82, v[2:5] offset:17024
	v_pk_mul_f32 v[2:3], v[6:7], v[0:1] op_sel_hi:[1,0]
	v_pk_mul_f32 v[4:5], v[8:9], v[0:1] op_sel_hi:[1,0]
	ds_write_b128 v82, v[2:5] offset:17056
	v_pk_mul_f32 v[2:3], v[10:11], v[0:1] op_sel_hi:[1,0]
	v_pk_mul_f32 v[4:5], v[12:13], v[0:1] op_sel_hi:[1,0]
	v_add_u32_e32 v8, s45, v79
	ds_write_b128 v82, v[2:5] offset:17088
	v_pk_mul_f32 v[2:3], v[14:15], v[0:1] op_sel_hi:[1,0]
	v_pk_mul_f32 v[4:5], v[16:17], v[0:1] op_sel_hi:[1,0]
	v_lshlrev_b32_e32 v0, 2, v66
	v_ashrrev_i32_e32 v9, 31, v8
	ds_write_b128 v82, v[2:5] offset:17120
	v_lshl_add_u64 v[2:3], s[40:41], 0, v[0:1]
	v_mov_b32_e32 v7, s1
	v_or_b32_e32 v6, s0, v66
	v_lshlrev_b64 v[4:5], 10, v[8:9]
	s_movk_i32 s0, 0x2000
	v_lshl_add_u64 v[4:5], v[4:5], 0, v[6:7]
	v_add_co_u32_e32 v2, vcc, s0, v2
	v_lshlrev_b64 v[18:19], 2, v[4:5]
	s_nop 0
	v_addc_co_u32_e32 v3, vcc, 0, v3, vcc
	s_waitcnt lgkmcnt(0)
	s_barrier
	global_load_dwordx4 v[2:5], v[2:3], off
	v_lshl_add_u64 v[10:11], s[72:73], 0, v[18:19]
	global_load_dwordx4 v[10:13], v[10:11], off
	v_add_u32_e32 v14, 8, v8
	v_ashrrev_i32_e32 v15, 31, v14
	v_lshlrev_b64 v[14:15], 10, v[14:15]
	v_lshl_add_u64 v[20:21], v[14:15], 0, v[6:7]
	ds_read_b128 v[14:17], v83
	v_lshlrev_b64 v[22:23], 2, v[20:21]
	v_lshl_add_u64 v[24:25], s[90:91], 0, v[18:19]
	ds_read_b128 v[18:21], v83 offset:4224
	v_lshl_add_u64 v[26:27], s[72:73], 0, v[22:23]
	s_mov_b64 s[40:41], 0
	s_waitcnt vmcnt(1) lgkmcnt(1)
	v_pk_mul_f32 v[14:15], v[2:3], v[14:15]
	v_pk_mul_f32 v[16:17], v[4:5], v[16:17]
	s_waitcnt vmcnt(0)
	v_pk_fma_f32 v[10:11], v[10:11], s[34:35], v[14:15] op_sel_hi:[1,0,1]
	v_pk_fma_f32 v[12:13], v[12:13], s[34:35], v[16:17] op_sel_hi:[1,0,1]
	global_store_dwordx4 v[24:25], v[10:13], off
	global_load_dwordx4 v[10:13], v[26:27], off
	v_add_u32_e32 v14, 16, v8
	v_ashrrev_i32_e32 v15, 31, v14
	v_lshlrev_b64 v[14:15], 10, v[14:15]
	v_lshl_add_u64 v[14:15], v[14:15], 0, v[6:7]
	s_waitcnt lgkmcnt(0)
	v_pk_mul_f32 v[18:19], v[2:3], v[18:19]
	v_pk_mul_f32 v[20:21], v[4:5], v[20:21]
	v_lshlrev_b64 v[24:25], 2, v[14:15]
	v_lshl_add_u64 v[14:15], s[90:91], 0, v[22:23]
	v_lshl_add_u64 v[16:17], s[72:73], 0, v[24:25]
	v_lshl_add_u64 v[24:25], s[90:91], 0, v[24:25]
	s_waitcnt vmcnt(0)
	v_pk_fma_f32 v[10:11], v[10:11], s[34:35], v[18:19] op_sel_hi:[1,0,1]
	v_pk_fma_f32 v[12:13], v[12:13], s[34:35], v[20:21] op_sel_hi:[1,0,1]
	global_store_dwordx4 v[14:15], v[10:13], off
	global_load_dwordx4 v[10:13], v[16:17], off
	v_add_u32_e32 v14, 24, v8
	v_ashrrev_i32_e32 v15, 31, v14
	v_lshlrev_b64 v[14:15], 10, v[14:15]
	v_lshl_add_u64 v[18:19], v[14:15], 0, v[6:7]
	ds_read_b128 v[14:17], v83 offset:8448
	v_lshlrev_b64 v[22:23], 2, v[18:19]
	ds_read_b128 v[18:21], v83 offset:12672
	v_lshl_add_u64 v[26:27], s[72:73], 0, v[22:23]
	s_waitcnt lgkmcnt(1)
	v_pk_mul_f32 v[14:15], v[2:3], v[14:15]
	v_pk_mul_f32 v[16:17], v[4:5], v[16:17]
	s_waitcnt lgkmcnt(0)
	v_pk_mul_f32 v[18:19], v[2:3], v[18:19]
	v_pk_mul_f32 v[20:21], v[4:5], v[20:21]
	s_waitcnt vmcnt(0)
; __device__ void phase_gemm_out(const Params& p, int bid, int nb, char* lds, const TileMap& tm) {
;     ...
;     {
;       const int c32 = tid & 31, r0 = tid >> 5;
;       const float4 gt = *(const float4*)(gate + c32 * 4);
; #pragma unroll
;       for (int q = 0; q < 16; ++q) {
;         const int row = r0 + 8 * q;
;         const size_t idx = (size_t)(m0 + row) * 1024 + n0 + c32 * 4;
;         const float4 xv = *(const float4*)(p.x + idx);
;         const float4 mv = *(const float4*)(stf + row * 132 + c32 * 4);
;         *(float4*)(p.out + idx) = make_float4(ALPHA * xv.x + gt.x * mv.x, ALPHA * xv.y + gt.y * mv.y, ALPHA * xv.z + gt.z * mv.z, ALPHA * xv.w + gt.w * mv.w);
;       }
;     }
	v_pk_fma_f32 v[10:11], v[10:11], s[34:35], v[14:15] op_sel_hi:[1,0,1]
	v_pk_fma_f32 v[12:13], v[12:13], s[34:35], v[16:17] op_sel_hi:[1,0,1]
	global_store_dwordx4 v[24:25], v[10:13], off
	global_load_dwordx4 v[10:13], v[26:27], off
	v_add_u32_e32 v14, 32, v8
	v_ashrrev_i32_e32 v15, 31, v14
	v_lshlrev_b64 v[14:15], 10, v[14:15]
	v_lshl_add_u64 v[14:15], v[14:15], 0, v[6:7]
	v_lshlrev_b64 v[24:25], 2, v[14:15]
	v_lshl_add_u64 v[14:15], s[90:91], 0, v[22:23]
	v_lshl_add_u64 v[16:17], s[72:73], 0, v[24:25]
	v_lshl_add_u64 v[24:25], s[90:91], 0, v[24:25]
	s_waitcnt vmcnt(0)
	v_pk_fma_f32 v[10:11], v[10:11], s[34:35], v[18:19] op_sel_hi:[1,0,1]
	v_pk_fma_f32 v[12:13], v[12:13], s[34:35], v[20:21] op_sel_hi:[1,0,1]
	global_store_dwordx4 v[14:15], v[10:13], off
	global_load_dwordx4 v[10:13], v[16:17], off
	v_add_u32_e32 v14, 40, v8
	v_ashrrev_i32_e32 v15, 31, v14
	v_lshlrev_b64 v[14:15], 10, v[14:15]
	v_lshl_add_u64 v[18:19], v[14:15], 0, v[6:7]
	ds_read_b128 v[14:17], v83 offset:16896
	v_lshlrev_b64 v[22:23], 2, v[18:19]
	ds_read_b128 v[18:21], v83 offset:21120
	v_lshl_add_u64 v[26:27], s[72:73], 0, v[22:23]
	s_waitcnt lgkmcnt(1)
	v_pk_mul_f32 v[14:15], v[2:3], v[14:15]
	v_pk_mul_f32 v[16:17], v[4:5], v[16:17]
	s_waitcnt lgkmcnt(0)
	v_pk_mul_f32 v[18:19], v[2:3], v[18:19]
	v_pk_mul_f32 v[20:21], v[4:5], v[20:21]
	s_waitcnt vmcnt(0)
	v_pk_fma_f32 v[10:11], v[10:11], s[34:35], v[14:15] op_sel_hi:[1,0,1]
	v_pk_fma_f32 v[12:13], v[12:13], s[34:35], v[16:17] op_sel_hi:[1,0,1]
	global_store_dwordx4 v[24:25], v[10:13], off
	global_load_dwordx4 v[10:13], v[26:27], off
	v_add_u32_e32 v14, 48, v8
	v_ashrrev_i32_e32 v15, 31, v14
	v_lshlrev_b64 v[14:15], 10, v[14:15]
	v_lshl_add_u64 v[14:15], v[14:15], 0, v[6:7]
	v_lshlrev_b64 v[24:25], 2, v[14:15]
	v_lshl_add_u64 v[14:15], s[90:91], 0, v[22:23]
	v_lshl_add_u64 v[16:17], s[72:73], 0, v[24:25]
	v_lshl_add_u64 v[24:25], s[90:91], 0, v[24:25]
	s_waitcnt vmcnt(0)
	v_pk_fma_f32 v[10:11], v[10:11], s[34:35], v[18:19] op_sel_hi:[1,0,1]
	v_pk_fma_f32 v[12:13], v[12:13], s[34:35], v[20:21] op_sel_hi:[1,0,1]
	global_store_dwordx4 v[14:15], v[10:13], off
	global_load_dwordx4 v[10:13], v[16:17], off
	v_add_u32_e32 v14, 56, v8
	v_ashrrev_i32_e32 v15, 31, v14
	v_lshlrev_b64 v[14:15], 10, v[14:15]
	v_lshl_add_u64 v[18:19], v[14:15], 0, v[6:7]
	ds_read_b128 v[14:17], v83 offset:25344
	v_lshlrev_b64 v[22:23], 2, v[18:19]
	ds_read_b128 v[18:21], v83 offset:29568
	v_lshl_add_u64 v[26:27], s[72:73], 0, v[22:23]
	s_waitcnt lgkmcnt(1)
	v_pk_mul_f32 v[14:15], v[2:3], v[14:15]
	v_pk_mul_f32 v[16:17], v[4:5], v[16:17]
	s_waitcnt lgkmcnt(0)
	v_pk_mul_f32 v[18:19], v[2:3], v[18:19]
	v_pk_mul_f32 v[20:21], v[4:5], v[20:21]
	s_waitcnt vmcnt(0)
	v_pk_fma_f32 v[10:11], v[10:11], s[34:35], v[14:15] op_sel_hi:[1,0,1]
	v_pk_fma_f32 v[12:13], v[12:13], s[34:35], v[16:17] op_sel_hi:[1,0,1]
	global_store_dwordx4 v[24:25], v[10:13], off
	global_load_dwordx4 v[10:13], v[26:27], off
	v_add_u32_e32 v14, 64, v8
	v_ashrrev_i32_e32 v15, 31, v14
	v_lshlrev_b64 v[14:15], 10, v[14:15]
	v_lshl_add_u64 v[14:15], v[14:15], 0, v[6:7]
	v_lshlrev_b64 v[24:25], 2, v[14:15]
	v_lshl_add_u64 v[14:15], s[90:91], 0, v[22:23]
	v_lshl_add_u64 v[16:17], s[72:73], 0, v[24:25]
	v_lshl_add_u64 v[24:25], s[90:91], 0, v[24:25]
	s_waitcnt vmcnt(0)
	v_pk_fma_f32 v[10:11], v[10:11], s[34:35], v[18:19] op_sel_hi:[1,0,1]
	v_pk_fma_f32 v[12:13], v[12:13], s[34:35], v[20:21] op_sel_hi:[1,0,1]
	global_store_dwordx4 v[14:15], v[10:13], off
	global_load_dwordx4 v[10:13], v[16:17], off
	v_add_u32_e32 v14, 0x48, v8
	v_ashrrev_i32_e32 v15, 31, v14
	v_lshlrev_b64 v[14:15], 10, v[14:15]
	v_lshl_add_u64 v[18:19], v[14:15], 0, v[6:7]
	ds_read_b128 v[14:17], v83 offset:33792
	v_lshlrev_b64 v[22:23], 2, v[18:19]
	ds_read_b128 v[18:21], v83 offset:38016
	v_lshl_add_u64 v[26:27], s[72:73], 0, v[22:23]
	s_waitcnt lgkmcnt(1)
	v_pk_mul_f32 v[14:15], v[2:3], v[14:15]
	v_pk_mul_f32 v[16:17], v[4:5], v[16:17]
	s_waitcnt lgkmcnt(0)
	v_pk_mul_f32 v[18:19], v[2:3], v[18:19]
	v_pk_mul_f32 v[20:21], v[4:5], v[20:21]
	s_waitcnt vmcnt(0)
; __device__ void phase_gemm_out(const Params& p, int bid, int nb, char* lds, const TileMap& tm) {
;     ...
;     {
;       const int c32 = tid & 31, r0 = tid >> 5;
;       const float4 gt = *(const float4*)(gate + c32 * 4);
; #pragma unroll
;       for (int q = 0; q < 16; ++q) {
;         const int row = r0 + 8 * q;
;         const size_t idx = (size_t)(m0 + row) * 1024 + n0 + c32 * 4;
;         const float4 xv = *(const float4*)(p.x + idx);
;         const float4 mv = *(const float4*)(stf + row * 132 + c32 * 4);
;         *(float4*)(p.out + idx) = make_float4(ALPHA * xv.x + gt.x * mv.x, ALPHA * xv.y + gt.y * mv.y, ALPHA * xv.z + gt.z * mv.z, ALPHA * xv.w + gt.w * mv.w);
;       }
;     }
;     __syncthreads();
	v_pk_fma_f32 v[10:11], v[10:11], s[34:35], v[14:15] op_sel_hi:[1,0,1]
	v_pk_fma_f32 v[12:13], v[12:13], s[34:35], v[16:17] op_sel_hi:[1,0,1]
	global_store_dwordx4 v[24:25], v[10:13], off
	global_load_dwordx4 v[10:13], v[26:27], off
	v_add_u32_e32 v14, 0x50, v8
	v_ashrrev_i32_e32 v15, 31, v14
	v_lshlrev_b64 v[14:15], 10, v[14:15]
	v_lshl_add_u64 v[14:15], v[14:15], 0, v[6:7]
	v_lshlrev_b64 v[24:25], 2, v[14:15]
	v_lshl_add_u64 v[14:15], s[90:91], 0, v[22:23]
	v_lshl_add_u64 v[16:17], s[72:73], 0, v[24:25]
	v_lshl_add_u64 v[24:25], s[90:91], 0, v[24:25]
	s_waitcnt vmcnt(0)
	v_pk_fma_f32 v[10:11], v[10:11], s[34:35], v[18:19] op_sel_hi:[1,0,1]
	v_pk_fma_f32 v[12:13], v[12:13], s[34:35], v[20:21] op_sel_hi:[1,0,1]
	global_store_dwordx4 v[14:15], v[10:13], off
	global_load_dwordx4 v[10:13], v[16:17], off
	v_add_u32_e32 v14, 0x58, v8
	v_ashrrev_i32_e32 v15, 31, v14
	v_lshlrev_b64 v[14:15], 10, v[14:15]
	v_lshl_add_u64 v[18:19], v[14:15], 0, v[6:7]
	ds_read_b128 v[14:17], v83 offset:42240
	v_lshlrev_b64 v[22:23], 2, v[18:19]
	ds_read_b128 v[18:21], v83 offset:46464
	v_lshl_add_u64 v[26:27], s[72:73], 0, v[22:23]
	s_waitcnt lgkmcnt(1)
	v_pk_mul_f32 v[14:15], v[2:3], v[14:15]
	v_pk_mul_f32 v[16:17], v[4:5], v[16:17]
	s_waitcnt lgkmcnt(0)
	v_pk_mul_f32 v[18:19], v[2:3], v[18:19]
	v_pk_mul_f32 v[20:21], v[4:5], v[20:21]
	s_waitcnt vmcnt(0)
	v_pk_fma_f32 v[10:11], v[10:11], s[34:35], v[14:15] op_sel_hi:[1,0,1]
	v_pk_fma_f32 v[12:13], v[12:13], s[34:35], v[16:17] op_sel_hi:[1,0,1]
	global_store_dwordx4 v[24:25], v[10:13], off
	global_load_dwordx4 v[10:13], v[26:27], off
	v_add_u32_e32 v14, 0x60, v8
	v_ashrrev_i32_e32 v15, 31, v14
	v_lshlrev_b64 v[14:15], 10, v[14:15]
	v_lshl_add_u64 v[14:15], v[14:15], 0, v[6:7]
	v_lshlrev_b64 v[24:25], 2, v[14:15]
	v_lshl_add_u64 v[14:15], s[90:91], 0, v[22:23]
	v_lshl_add_u64 v[16:17], s[72:73], 0, v[24:25]
	v_lshl_add_u64 v[24:25], s[90:91], 0, v[24:25]
	s_waitcnt vmcnt(0)
	v_pk_fma_f32 v[10:11], v[10:11], s[34:35], v[18:19] op_sel_hi:[1,0,1]
	v_pk_fma_f32 v[12:13], v[12:13], s[34:35], v[20:21] op_sel_hi:[1,0,1]
	global_store_dwordx4 v[14:15], v[10:13], off
	global_load_dwordx4 v[10:13], v[16:17], off
	v_add_u32_e32 v14, 0x68, v8
	v_ashrrev_i32_e32 v15, 31, v14
	v_lshlrev_b64 v[14:15], 10, v[14:15]
	v_lshl_add_u64 v[18:19], v[14:15], 0, v[6:7]
	ds_read_b128 v[14:17], v83 offset:50688
	v_lshlrev_b64 v[22:23], 2, v[18:19]
	ds_read_b128 v[18:21], v83 offset:54912
	v_lshl_add_u64 v[26:27], s[72:73], 0, v[22:23]
	s_waitcnt lgkmcnt(1)
	v_pk_mul_f32 v[14:15], v[2:3], v[14:15]
	v_pk_mul_f32 v[16:17], v[4:5], v[16:17]
	s_waitcnt lgkmcnt(0)
	v_pk_mul_f32 v[18:19], v[2:3], v[18:19]
	v_pk_mul_f32 v[20:21], v[4:5], v[20:21]
	s_waitcnt vmcnt(0)
	v_pk_fma_f32 v[10:11], v[10:11], s[34:35], v[14:15] op_sel_hi:[1,0,1]
	v_pk_fma_f32 v[12:13], v[12:13], s[34:35], v[16:17] op_sel_hi:[1,0,1]
	global_store_dwordx4 v[24:25], v[10:13], off
	global_load_dwordx4 v[10:13], v[26:27], off
	v_add_u32_e32 v14, 0x70, v8
	v_ashrrev_i32_e32 v15, 31, v14
	v_lshlrev_b64 v[14:15], 10, v[14:15]
	v_lshl_add_u64 v[14:15], v[14:15], 0, v[6:7]
	v_lshlrev_b64 v[14:15], 2, v[14:15]
	v_lshl_add_u64 v[16:17], s[90:91], 0, v[22:23]
	v_lshl_add_u64 v[22:23], s[72:73], 0, v[14:15]
	v_add_u32_e32 v8, 0x78, v8
	v_ashrrev_i32_e32 v9, 31, v8
	v_lshlrev_b64 v[8:9], 10, v[8:9]
	s_waitcnt vmcnt(0)
	v_pk_fma_f32 v[10:11], v[10:11], s[34:35], v[18:19] op_sel_hi:[1,0,1]
	v_pk_fma_f32 v[12:13], v[12:13], s[34:35], v[20:21] op_sel_hi:[1,0,1]
	global_store_dwordx4 v[16:17], v[10:13], off
	global_load_dwordx4 v[10:13], v[22:23], off
	v_lshl_add_u64 v[16:17], v[8:9], 0, v[6:7]
	ds_read_b128 v[6:9], v83 offset:59136
	v_lshlrev_b64 v[18:19], 2, v[16:17]
	v_lshl_add_u64 v[20:21], s[90:91], 0, v[14:15]
	ds_read_b128 v[14:17], v83 offset:63360
	v_lshl_add_u64 v[22:23], s[72:73], 0, v[18:19]
	s_waitcnt lgkmcnt(1)
	v_pk_mul_f32 v[6:7], v[2:3], v[6:7]
	v_pk_mul_f32 v[8:9], v[4:5], v[8:9]
	s_waitcnt lgkmcnt(0)
	v_pk_mul_f32 v[2:3], v[2:3], v[14:15]
	v_pk_mul_f32 v[4:5], v[4:5], v[16:17]
	s_waitcnt vmcnt(0)
	v_pk_fma_f32 v[6:7], v[10:11], s[34:35], v[6:7] op_sel_hi:[1,0,1]
	v_pk_fma_f32 v[8:9], v[12:13], s[34:35], v[8:9] op_sel_hi:[1,0,1]
	global_store_dwordx4 v[20:21], v[6:9], off
	global_load_dwordx4 v[6:9], v[22:23], off
	v_lshl_add_u64 v[10:11], s[90:91], 0, v[18:19]
	s_waitcnt vmcnt(0)
	v_pk_fma_f32 v[2:3], v[6:7], s[34:35], v[2:3] op_sel_hi:[1,0,1]
	v_pk_fma_f32 v[4:5], v[8:9], s[34:35], v[4:5] op_sel_hi:[1,0,1]
	global_store_dwordx4 v[10:11], v[2:5], off
	s_barrier

; DI int otid() { int t; asm volatile("v_mov_b32 %0, %1" : "=v"(t) : "v"((int)threadIdx.x)); return t; }
; template <bool RESCALE, bool SWAP>
; DI void gemm_mainloop_glds(const bf16_t* __restrict__ A, const bf16_t* __restrict__ Bt, int m0, int n0, char* lds,
;                            f32x16 (&acc)[2][2], const float* ratio_lds) {
;     ...
;   const int tid = otid(), lane = tid & 63, w = tid >> 6, wm = w >> 1, wn = w & 1, l31 = lane & 31, h = lane >> 5;
;   const int lr = lane >> 3, csrc = (lane & 7) ^ (4 * (w & 1) + (lr >> 1));
;   const bf16_t* ag = A + (size_t)(m0 + 8 * w + lr) * K + csrc * 8;
;   const bf16_t* bg = Bt + (size_t)(n0 + 8 * w + lr) * K + csrc * 8;
;   const unsigned lbase = (unsigned)(size_t)lds + (unsigned)w * 1024u;
;   const int swz = (l31 >> 1) & 7;
;   const char* fa = lds + (64 * wm + l31) * 128;
;   const char* fb = lds + OPB + (64 * wn + l31) * 128;
;   int fo[4];
; #pragma unroll
;   for (int s_ = 0; s_ < 4; ++s_) fo[s_] = ((2 * s_ + h) ^ swz) * 16;
;   f32x16 c00, c01, c10, c11;
; #pragma unroll
;   for (int r = 0; r < 16; ++r) { c00[r] = 0.f; c01[r] = 0.f; c10[r] = 0.f; c11[r] = 0.f; }
;     ...
;   D_ISSUE(0, 0);
;   __syncthreads();
.LBB0_321:
	s_setprio 1
	s_or_b64 exec, exec, s[40:41]
	v_mov_b32 v8, v118
	s_lshl_b32 s0, s42, 7
	v_ashrrev_i32_e32 v0, 6, v8
	v_and_b32_e32 v9, 1, v0
	v_bfe_u32 v10, v8, 3, 3
	v_and_b32_e32 v2, 7, v8
	v_lshlrev_b32_e32 v3, 2, v9
	v_bfe_u32 v4, v8, 4, 2
	v_lshlrev_b32_e32 v11, 3, v0
	v_bitop3_b32 v6, v3, v2, v4 bitop3:0x36
	v_or_b32_e32 v4, v10, v11
	v_add_u32_e32 v2, s45, v4
	v_ashrrev_i32_e32 v3, 31, v2
	v_add_u32_e32 v4, s0, v4
	v_lshlrev_b64 v[2:3], 11, v[2:3]
	v_ashrrev_i32_e32 v5, 31, v4
	v_lshlrev_b32_e32 v85, 10, v0
	v_lshlrev_b64 v[4:5], 11, v[4:5]
	v_lshl_add_u64 v[2:3], s[50:51], 0, v[2:3]
	v_lshlrev_b32_e32 v0, 4, v6
	v_add_u32_e32 v86, 0x4000, v85
	v_readfirstlane_b32 s1, v85
	v_lshl_add_u64 v[4:5], s[54:55], 0, v[4:5]
	v_lshl_add_u64 v[2:3], v[2:3], 0, v[0:1]
	s_mov_b32 m0, s1
	v_readfirstlane_b32 s1, v86
	v_add_u32_e32 v87, 0x1000, v85
	v_lshl_add_u64 v[4:5], v[4:5], 0, v[0:1]
	global_load_lds_dwordx4 v[2:3], off
	s_mov_b32 m0, s1
	v_readfirstlane_b32 s1, v87
	v_add_u32_e32 v88, 0x5000, v85
	global_load_lds_dwordx4 v[4:5], off
	v_lshl_add_u64 v[6:7], v[2:3], 0, s[22:23]
	s_mov_b32 m0, s1
	v_readfirstlane_b32 s1, v88
	v_add_u32_e32 v89, 0x2000, v85
	global_load_lds_dwordx4 v[6:7], off
	v_lshl_add_u64 v[6:7], v[4:5], 0, s[22:23]
	s_mov_b32 m0, s1
	v_readfirstlane_b32 s1, v89
	v_add_u32_e32 v90, 0x6000, v85
	global_load_lds_dwordx4 v[6:7], off
	v_lshl_add_u64 v[6:7], v[2:3], 0, s[26:27]
	s_mov_b32 m0, s1
	v_readfirstlane_b32 s1, v90
	v_add_u32_e32 v91, 0x3000, v85
	global_load_lds_dwordx4 v[6:7], off
	v_lshl_add_u64 v[6:7], v[4:5], 0, s[26:27]
	s_mov_b32 m0, s1
	v_readfirstlane_b32 s1, v91
	v_add_u32_e32 v92, 0x7000, v85
	global_load_lds_dwordx4 v[6:7], off
	v_lshl_add_u64 v[2:3], v[2:3], 0, s[28:29]
	s_mov_b32 m0, s1
	v_readfirstlane_b32 s1, v92
	global_load_lds_dwordx4 v[2:3], off
	v_lshl_add_u64 v[2:3], v[4:5], 0, s[28:29]
	s_mov_b32 m0, s1
	v_lshrrev_b32_e32 v4, 1, v8
	global_load_lds_dwordx4 v[2:3], off
	v_bfe_u32 v3, v8, 5, 1
	v_and_b32_e32 v2, 31, v8
	v_bfe_u32 v5, v8, 1, 3
	v_ashrrev_i32_e32 v6, 1, v8
	v_bitop3_b32 v4, v3, v4, 7 bitop3:0x78
	v_and_or_b32 v6, v6, s33, v2
	v_lshlrev_b32_e32 v94, 4, v4
	v_bitop3_b32 v4, v3, v5, 2 bitop3:0x36
	v_lshlrev_b32_e32 v2, 7, v2
	v_lshlrev_b32_e32 v95, 4, v4
	v_bitop3_b32 v4, v3, v5, 4 bitop3:0x36
	v_bitop3_b32 v3, v3, v5, 6 bitop3:0x36
	v_lshl_or_b32 v98, v9, 13, v2
	v_add3_u32 v2, v10, s45, v11
	v_lshlrev_b32_e32 v97, 4, v3
	v_ashrrev_i32_e32 v3, 31, v2
	v_lshlrev_b64 v[2:3], 11, v[2:3]
	v_or_b32_e32 v2, v2, v0
	v_lshl_add_u64 v[70:71], s[92:93], 0, v[2:3]
	v_or_b32_e32 v2, s0, v10
	v_add_u32_e32 v2, v2, v11
	v_ashrrev_i32_e32 v3, 31, v2
	v_lshlrev_b64 v[2:3], 11, v[2:3]
	v_or_b32_e32 v2, v2, v0
	v_mov_b32_e32 v14, v1
	v_mov_b32_e32 v15, v1
	v_lshlrev_b32_e32 v93, 7, v6
	v_lshlrev_b32_e32 v96, 4, v4
	v_lshl_add_u32 v99, v6, 2, v84
	v_lshl_add_u64 v[72:73], s[92:93], 0, v[2:3]
	v_mov_b32_e32 v0, v1
	v_mov_b32_e32 v2, v1
	v_mov_b32_e32 v3, v1
	v_mov_b32_e32 v4, v1
	v_mov_b32_e32 v5, v1
	v_mov_b32_e32 v6, v1
	v_mov_b32_e32 v7, v1
	v_mov_b32_e32 v8, v1
	v_mov_b32_e32 v9, v1
	v_mov_b32_e32 v10, v1
	v_mov_b32_e32 v11, v1
	v_mov_b32_e32 v12, v1
	v_mov_b32_e32 v13, v1
	v_mov_b64_e32 v[64:65], v[14:15]
	v_mov_b64_e32 v[48:49], v[14:15]
	v_mov_b64_e32 v[32:33], v[14:15]
	v_mov_b64_e32 v[62:63], v[12:13]
	v_mov_b64_e32 v[60:61], v[10:11]
	v_mov_b64_e32 v[58:59], v[8:9]
	v_mov_b64_e32 v[56:57], v[6:7]
	v_mov_b64_e32 v[54:55], v[4:5]
	v_mov_b64_e32 v[52:53], v[2:3]
	v_mov_b64_e32 v[50:51], v[0:1]
	v_mov_b64_e32 v[46:47], v[12:13]
	v_mov_b64_e32 v[44:45], v[10:11]
	v_mov_b64_e32 v[42:43], v[8:9]
	v_mov_b64_e32 v[40:41], v[6:7]
	v_mov_b64_e32 v[38:39], v[4:5]
	v_mov_b64_e32 v[36:37], v[2:3]
	v_mov_b64_e32 v[34:35], v[0:1]
	v_mov_b64_e32 v[30:31], v[12:13]
	v_mov_b64_e32 v[28:29], v[10:11]
	v_mov_b64_e32 v[26:27], v[8:9]
	v_mov_b64_e32 v[24:25], v[6:7]
	v_mov_b64_e32 v[22:23], v[4:5]
	v_mov_b64_e32 v[20:21], v[2:3]
	v_mov_b64_e32 v[18:19], v[0:1]
	v_mov_b64_e32 v[16:17], v[14:15]
	s_mov_b32 s1, 0
	s_mov_b64 s[40:41], 0
	v_add_u32_e32 v100, 0x8000, v85
	v_add_u32_e32 v101, 0xc000, v85
	v_add_u32_e32 v102, 0x9000, v85
	v_add_u32_e32 v103, 0xd000, v85
	v_add_u32_e32 v104, 0xa000, v85
	v_add_u32_e32 v105, 0xe000, v85
	v_add_u32_e32 v106, 0xb000, v85
	v_add_u32_e32 v107, 0xf000, v85
	v_mov_b64_e32 v[14:15], v[12:13]
	v_mov_b64_e32 v[12:13], v[10:11]
	v_mov_b64_e32 v[10:11], v[8:9]
	v_mov_b64_e32 v[8:9], v[6:7]
	v_mov_b64_e32 v[6:7], v[4:5]
	v_mov_b64_e32 v[4:5], v[2:3]
	v_mov_b64_e32 v[2:3], v[0:1]
	s_waitcnt vmcnt(0) lgkmcnt(0)
	s_barrier
	s_branch .LBB0_323

; DI int otid() { int t; asm volatile("v_mov_b32 %0, %1" : "=v"(t) : "v"((int)threadIdx.x)); return t; }
; template <bool RESCALE, bool SWAP>
; DI void gemm_mainloop_glds(const bf16_t* __restrict__ A, const bf16_t* __restrict__ Bt, int m0, int n0, char* lds,
;                            f32x16 (&acc)[2][2], const float* ratio_lds) {
;     ...
;   const int tid = otid(), lane = tid & 63, w = tid >> 6, wm = w >> 1, wn = w & 1, l31 = lane & 31, h = lane >> 5;
;   const int lr = lane >> 3, csrc = (lane & 7) ^ (4 * (w & 1) + (lr >> 1));
;   const bf16_t* ag = A + (size_t)(m0 + 8 * w + lr) * K + csrc * 8;
;   const bf16_t* bg = Bt + (size_t)(n0 + 8 * w + lr) * K + csrc * 8;
;   const unsigned lbase = (unsigned)(size_t)lds + (unsigned)w * 1024u;
;   const int swz = (l31 >> 1) & 7;
;   const char* fa = lds + (64 * wm + l31) * 128;
;   const char* fb = lds + OPB + (64 * wn + l31) * 128;
;   int fo[4];
; #pragma unroll
;   for (int s_ = 0; s_ < 4; ++s_) fo[s_] = ((2 * s_ + h) ^ swz) * 16;
;   f32x16 c00, c01, c10, c11;
; #pragma unroll
;   for (int r = 0; r < 16; ++r) { c00[r] = 0.f; c01[r] = 0.f; c10[r] = 0.f; c11[r] = 0.f; }
;     ...
;   D_ISSUE(0, 0);
;   __syncthreads();
.LBB0_449:
	s_setprio 1
	s_lshl_b32 s3, s68, 7
	s_lshl_b32 s0, s18, 7
	v_readlane_b32 s22, v182, 19
	v_readlane_b32 s23, v182, 20
	v_lshrrev_b32_e32 v119, 3, v118
	v_lshrrev_b32_e32 v120, 6, v118
	v_and_b32_e32 v121, 1, v120
	v_bfe_u32 v122, v118, 4, 2
	v_lshl_or_b32 v122, v121, 2, v122
	v_and_b32_e32 v123, 7, v118
	v_xor_b32_e32 v122, v122, v123
	v_lshlrev_b32_e32 v124, 10, v120
	v_add_u32_e32 v126, s3, v119
	v_add_u32_e32 v128, s0, v119
	v_readfirstlane_b32 s19, v124
	v_lshlrev_b32_e32 v126, 11, v126
	v_lshlrev_b32_e32 v128, 11, v128
	v_lshl_or_b32 v126, v122, 4, v126
	v_lshl_or_b32 v128, v122, 4, v128
	v_mov_b32_e32 v127, 0
	v_mov_b32_e32 v129, 0
	v_lshl_add_u64 v[86:87], v[126:127], 0, s[22:23]
	v_readlane_b32 s22, v183, 2
	v_readlane_b32 s23, v183, 3
	s_nop 1
	v_lshl_add_u64 v[88:89], v[128:129], 0, s[22:23]
	v_lshl_add_u64 v[90:91], v[86:87], 0, s[34:35]
	v_lshl_add_u64 v[136:137], v[86:87], 0, s[58:59]
	v_lshl_add_u64 v[140:141], v[86:87], 0, s[60:61]
	v_lshl_add_u64 v[92:93], v[88:89], 0, s[34:35]
	v_lshl_add_u64 v[138:139], v[88:89], 0, s[58:59]
	v_lshl_add_u64 v[142:143], v[88:89], 0, s[60:61]
	v_mov_b32_e32 v130, 0x80
	v_mov_b32_e32 v131, 0
	s_mov_b32 m0, s19
	s_nop 0
	global_load_lds_dwordx4 v[86:87], off
	s_add_u32 m0, s19, 0x4000
	s_nop 0
	global_load_lds_dwordx4 v[88:89], off
	s_add_u32 m0, s19, 0x1000
	s_nop 0
	global_load_lds_dwordx4 v[90:91], off
	s_add_u32 m0, s19, 0x5000
	s_nop 0
	global_load_lds_dwordx4 v[92:93], off
	s_add_u32 m0, s19, 0x2000
	s_nop 0
	global_load_lds_dwordx4 v[136:137], off
	s_add_u32 m0, s19, 0x6000
	s_nop 0
	global_load_lds_dwordx4 v[138:139], off
	s_add_u32 m0, s19, 0x3000
	s_nop 0
	global_load_lds_dwordx4 v[140:141], off
	s_add_u32 m0, s19, 0x7000
	s_nop 0
	global_load_lds_dwordx4 v[142:143], off
	s_add_u32 m0, s19, 0x8000
	v_lshl_add_u64 v[86:87], v[130:131], 0, v[86:87]
	global_load_lds_dwordx4 v[86:87], off
	s_add_u32 m0, s19, 0xc000
	v_lshl_add_u64 v[88:89], v[130:131], 0, v[88:89]
	global_load_lds_dwordx4 v[88:89], off
	s_add_u32 m0, s19, 0x9000
	v_lshl_add_u64 v[90:91], v[130:131], 0, v[90:91]
	global_load_lds_dwordx4 v[90:91], off
	s_add_u32 m0, s19, 0xd000
	v_lshl_add_u64 v[92:93], v[130:131], 0, v[92:93]
	global_load_lds_dwordx4 v[92:93], off
	s_add_u32 m0, s19, 0xa000
	v_lshl_add_u64 v[136:137], v[130:131], 0, v[136:137]
	global_load_lds_dwordx4 v[136:137], off
	s_add_u32 m0, s19, 0xe000
	v_lshl_add_u64 v[138:139], v[130:131], 0, v[138:139]
	global_load_lds_dwordx4 v[138:139], off
	s_add_u32 m0, s19, 0xb000
	v_lshl_add_u64 v[140:141], v[130:131], 0, v[140:141]
	global_load_lds_dwordx4 v[140:141], off
	s_add_u32 m0, s19, 0xf000
	v_lshl_add_u64 v[142:143], v[130:131], 0, v[142:143]
	global_load_lds_dwordx4 v[142:143], off
	v_and_b32_e32 v119, 31, v118
	v_bfe_u32 v120, v118, 5, 1
	v_bfe_u32 v121, v118, 1, 3
	v_lshrrev_b32_e32 v122, 7, v118
	v_bfe_u32 v123, v118, 6, 1
	v_lshl_or_b32 v122, v122, 6, v119
	v_lshl_or_b32 v123, v123, 6, v119
	v_lshlrev_b32_e32 v122, 7, v122
	v_lshlrev_b32_e32 v123, 7, v123
	v_or_b32_e32 v124, 0, v120
	v_xor_b32_e32 v124, v124, v121
	v_lshl_add_u32 v109, v124, 4, v122
	v_lshl_add_u32 v113, v124, 4, v123
	v_or_b32_e32 v124, 2, v120
	v_xor_b32_e32 v124, v124, v121
	v_lshl_add_u32 v110, v124, 4, v122
	v_lshl_add_u32 v115, v124, 4, v123
	v_or_b32_e32 v124, 4, v120
	v_xor_b32_e32 v124, v124, v121
	v_lshl_add_u32 v111, v124, 4, v122
	v_lshl_add_u32 v116, v124, 4, v123
	v_or_b32_e32 v124, 6, v120
	v_xor_b32_e32 v124, v124, v121
	v_lshl_add_u32 v112, v124, 4, v122
	v_lshl_add_u32 v117, v124, 4, v123
	v_mov_b32_e32 v0, 0
	v_mov_b32_e32 v1, 0
	v_mov_b32_e32 v2, 0
	v_mov_b32_e32 v3, 0
	v_mov_b32_e32 v4, 0
	v_mov_b32_e32 v5, 0
	v_mov_b32_e32 v6, 0
	v_mov_b32_e32 v7, 0
	v_mov_b32_e32 v8, 0
	v_mov_b32_e32 v9, 0
	v_mov_b32_e32 v10, 0
	v_mov_b32_e32 v11, 0
	v_mov_b32_e32 v12, 0
	v_mov_b32_e32 v13, 0
	v_mov_b32_e32 v14, 0
	v_mov_b32_e32 v15, 0
	v_mov_b32_e32 v16, 0
	v_mov_b32_e32 v17, 0
	v_mov_b32_e32 v18, 0
	v_mov_b32_e32 v19, 0
	v_mov_b32_e32 v20, 0
	v_mov_b32_e32 v21, 0
	v_mov_b32_e32 v22, 0
	v_mov_b32_e32 v23, 0
	v_mov_b32_e32 v24, 0
	v_mov_b32_e32 v25, 0
	v_mov_b32_e32 v26, 0
	v_mov_b32_e32 v27, 0
	v_mov_b32_e32 v28, 0
	v_mov_b32_e32 v29, 0
	v_mov_b32_e32 v30, 0
	v_mov_b32_e32 v31, 0
	v_mov_b32_e32 v32, 0
	v_mov_b32_e32 v33, 0
	v_mov_b32_e32 v34, 0
	v_mov_b32_e32 v35, 0
	v_mov_b32_e32 v36, 0
	v_mov_b32_e32 v37, 0
	v_mov_b32_e32 v38, 0
	v_mov_b32_e32 v39, 0
	v_mov_b32_e32 v40, 0
	v_mov_b32_e32 v41, 0
	v_mov_b32_e32 v42, 0
	v_mov_b32_e32 v43, 0
	v_mov_b32_e32 v44, 0
	v_mov_b32_e32 v45, 0
	v_mov_b32_e32 v46, 0
	v_mov_b32_e32 v47, 0
	v_mov_b32_e32 v48, 0
	v_mov_b32_e32 v49, 0
	v_mov_b32_e32 v50, 0
	v_mov_b32_e32 v51, 0
	v_mov_b32_e32 v52, 0
	v_mov_b32_e32 v53, 0
	v_mov_b32_e32 v54, 0
	v_mov_b32_e32 v55, 0
	v_mov_b32_e32 v56, 0
	v_mov_b32_e32 v57, 0
	v_mov_b32_e32 v58, 0
	v_mov_b32_e32 v59, 0
	v_mov_b32_e32 v60, 0
	v_mov_b32_e32 v61, 0
	v_mov_b32_e32 v62, 0
	v_mov_b32_e32 v63, 0
	s_mov_b32 s1, 0
	s_waitcnt vmcnt(8)
	s_barrier
; DI int crow(int r, int h) { return (r & 3) + 8 * (r >> 2) + 4 * h; }
; #define D_COMPUTE(BUF) { D_MMA1(BUF, 0) D_MMA1(BUF, 1) D_MMA1(BUF, 2) D_MMA1(BUF, 3) }
; template <bool RESCALE, bool SWAP>
; DI void gemm_mainloop_glds(const bf16_t* __restrict__ A, const bf16_t* __restrict__ Bt, int m0, int n0, char* lds,
;                            f32x16 (&acc)[2][2], const float* ratio_lds) {
;     ...
;   for (int kt = 0; kt < NK; kt += 2) {
;     D_ISSUE(1, kt + 1);
;     if (RESCALE) {
;       if (kt == NK / 2) {
;         if (SWAP) {
;           const float sc0_ = ratio_lds[64 * wm + l31], sc1_ = ratio_lds[64 * wm + 32 + l31];
; #pragma unroll
;           for (int r = 0; r < 16; ++r) { c00[r] *= sc0_; c10[r] *= sc0_; c01[r] *= sc1_; c11[r] *= sc1_; }
;         } else {
; #pragma unroll
;           for (int r = 0; r < 16; ++r) {
;             float sc0_ = ratio_lds[64 * wm + crow(r, h)], sc1_ = ratio_lds[64 * wm + 32 + crow(r, h)];
;             c00[r] *= sc0_; c01[r] *= sc0_; c10[r] *= sc1_; c11[r] *= sc1_;
;           }
;         }
;       }
;     }
;     D_COMPUTE(0);
;     __syncthreads();
;     if (kt + 2 < NK) D_ISSUE(0, kt + 2);
;     D_COMPUTE(1);
;     __syncthreads();
;   }
.Lgm_pq_loop:
	ds_read_b128 v[184:187], v109
	ds_read_b128 v[188:191], v109 offset:4096
	ds_read_b128 v[192:195], v113 offset:16384
	ds_read_b128 v[196:199], v113 offset:20480
	ds_read_b128 v[200:203], v110
	ds_read_b128 v[204:207], v110 offset:4096
	ds_read_b128 v[208:211], v115 offset:16384
	ds_read_b128 v[212:215], v115 offset:20480
	ds_read_b128 v[216:219], v111
	ds_read_b128 v[220:223], v111 offset:4096
	ds_read_b128 v[224:227], v116 offset:16384
	ds_read_b128 v[228:231], v116 offset:20480
	ds_read_b128 v[232:235], v112
	ds_read_b128 v[236:239], v112 offset:4096
	ds_read_b128 v[240:243], v117 offset:16384
	ds_read_b128 v[244:247], v117 offset:20480
	s_waitcnt lgkmcnt(0)
	s_barrier
	s_mov_b32 m0, s19
	v_lshl_add_u64 v[86:87], v[130:131], 0, v[86:87]
	global_load_lds_dwordx4 v[86:87], off
	s_add_u32 m0, s19, 0x4000
	v_lshl_add_u64 v[88:89], v[130:131], 0, v[88:89]
	global_load_lds_dwordx4 v[88:89], off
	s_add_u32 m0, s19, 0x1000
	v_lshl_add_u64 v[90:91], v[130:131], 0, v[90:91]
	global_load_lds_dwordx4 v[90:91], off
	s_add_u32 m0, s19, 0x5000
	v_lshl_add_u64 v[92:93], v[130:131], 0, v[92:93]
	global_load_lds_dwordx4 v[92:93], off
	s_add_u32 m0, s19, 0x2000
	v_lshl_add_u64 v[136:137], v[130:131], 0, v[136:137]
	global_load_lds_dwordx4 v[136:137], off
	s_add_u32 m0, s19, 0x6000
	v_lshl_add_u64 v[138:139], v[130:131], 0, v[138:139]
	global_load_lds_dwordx4 v[138:139], off
	s_add_u32 m0, s19, 0x3000
	v_lshl_add_u64 v[140:141], v[130:131], 0, v[140:141]
	global_load_lds_dwordx4 v[140:141], off
	s_add_u32 m0, s19, 0x7000
	v_lshl_add_u64 v[142:143], v[130:131], 0, v[142:143]
	global_load_lds_dwordx4 v[142:143], off
	v_mfma_f32_32x32x16_bf16 v[0:15], v[192:195], v[184:187], v[0:15]
	v_mfma_f32_32x32x16_bf16 v[16:31], v[192:195], v[188:191], v[16:31]
	v_mfma_f32_32x32x16_bf16 v[32:47], v[196:199], v[184:187], v[32:47]
	v_mfma_f32_32x32x16_bf16 v[48:63], v[196:199], v[188:191], v[48:63]
	v_mfma_f32_32x32x16_bf16 v[0:15], v[208:211], v[200:203], v[0:15]
	v_mfma_f32_32x32x16_bf16 v[16:31], v[208:211], v[204:207], v[16:31]
	v_mfma_f32_32x32x16_bf16 v[32:47], v[212:215], v[200:203], v[32:47]
	v_mfma_f32_32x32x16_bf16 v[48:63], v[212:215], v[204:207], v[48:63]
	v_mfma_f32_32x32x16_bf16 v[0:15], v[224:227], v[216:219], v[0:15]
	v_mfma_f32_32x32x16_bf16 v[16:31], v[224:227], v[220:223], v[16:31]
	v_mfma_f32_32x32x16_bf16 v[32:47], v[228:231], v[216:219], v[32:47]
	v_mfma_f32_32x32x16_bf16 v[48:63], v[228:231], v[220:223], v[48:63]
	v_mfma_f32_32x32x16_bf16 v[0:15], v[240:243], v[232:235], v[0:15]
	v_mfma_f32_32x32x16_bf16 v[16:31], v[240:243], v[236:239], v[16:31]
	v_mfma_f32_32x32x16_bf16 v[32:47], v[244:247], v[232:235], v[32:47]
	v_mfma_f32_32x32x16_bf16 v[48:63], v[244:247], v[236:239], v[48:63]
	s_waitcnt vmcnt(8)
	s_barrier
	ds_read_b128 v[184:187], v109 offset:32768
	ds_read_b128 v[188:191], v109 offset:36864
	ds_read_b128 v[192:195], v113 offset:49152
	ds_read_b128 v[196:199], v113 offset:53248
	ds_read_b128 v[200:203], v110 offset:32768
	ds_read_b128 v[204:207], v110 offset:36864
	ds_read_b128 v[208:211], v115 offset:49152
	ds_read_b128 v[212:215], v115 offset:53248
	ds_read_b128 v[216:219], v111 offset:32768
	ds_read_b128 v[220:223], v111 offset:36864
	ds_read_b128 v[224:227], v116 offset:49152
	ds_read_b128 v[228:231], v116 offset:53248
	ds_read_b128 v[232:235], v112 offset:32768
	ds_read_b128 v[236:239], v112 offset:36864
	ds_read_b128 v[240:243], v117 offset:49152
	ds_read_b128 v[244:247], v117 offset:53248
	s_waitcnt lgkmcnt(0)
	s_barrier
	s_add_u32 m0, s19, 0x8000
	v_lshl_add_u64 v[86:87], v[130:131], 0, v[86:87]
	global_load_lds_dwordx4 v[86:87], off
	s_add_u32 m0, s19, 0xc000
	v_lshl_add_u64 v[88:89], v[130:131], 0, v[88:89]
	global_load_lds_dwordx4 v[88:89], off
	s_add_u32 m0, s19, 0x9000
	v_lshl_add_u64 v[90:91], v[130:131], 0, v[90:91]
	global_load_lds_dwordx4 v[90:91], off
	s_add_u32 m0, s19, 0xd000
	v_lshl_add_u64 v[92:93], v[130:131], 0, v[92:93]
	global_load_lds_dwordx4 v[92:93], off
	s_add_u32 m0, s19, 0xa000
	v_lshl_add_u64 v[136:137], v[130:131], 0, v[136:137]
	global_load_lds_dwordx4 v[136:137], off
	s_add_u32 m0, s19, 0xe000
	v_lshl_add_u64 v[138:139], v[130:131], 0, v[138:139]
	global_load_lds_dwordx4 v[138:139], off
	s_add_u32 m0, s19, 0xb000
	v_lshl_add_u64 v[140:141], v[130:131], 0, v[140:141]
	global_load_lds_dwordx4 v[140:141], off
	s_add_u32 m0, s19, 0xf000
	v_lshl_add_u64 v[142:143], v[130:131], 0, v[142:143]
	global_load_lds_dwordx4 v[142:143], off
	v_mfma_f32_32x32x16_bf16 v[0:15], v[192:195], v[184:187], v[0:15]
	v_mfma_f32_32x32x16_bf16 v[16:31], v[192:195], v[188:191], v[16:31]
	v_mfma_f32_32x32x16_bf16 v[32:47], v[196:199], v[184:187], v[32:47]
	v_mfma_f32_32x32x16_bf16 v[48:63], v[196:199], v[188:191], v[48:63]
	v_mfma_f32_32x32x16_bf16 v[0:15], v[208:211], v[200:203], v[0:15]
	v_mfma_f32_32x32x16_bf16 v[16:31], v[208:211], v[204:207], v[16:31]
	v_mfma_f32_32x32x16_bf16 v[32:47], v[212:215], v[200:203], v[32:47]
	v_mfma_f32_32x32x16_bf16 v[48:63], v[212:215], v[204:207], v[48:63]
	v_mfma_f32_32x32x16_bf16 v[0:15], v[224:227], v[216:219], v[0:15]
	v_mfma_f32_32x32x16_bf16 v[16:31], v[224:227], v[220:223], v[16:31]
	v_mfma_f32_32x32x16_bf16 v[32:47], v[228:231], v[216:219], v[32:47]
	v_mfma_f32_32x32x16_bf16 v[48:63], v[228:231], v[220:223], v[48:63]
	v_mfma_f32_32x32x16_bf16 v[0:15], v[240:243], v[232:235], v[0:15]
	v_mfma_f32_32x32x16_bf16 v[16:31], v[240:243], v[236:239], v[16:31]
	v_mfma_f32_32x32x16_bf16 v[32:47], v[244:247], v[232:235], v[32:47]
	v_mfma_f32_32x32x16_bf16 v[48:63], v[244:247], v[236:239], v[48:63]
	s_waitcnt vmcnt(8)
	s_barrier
; DI int crow(int r, int h) { return (r & 3) + 8 * (r >> 2) + 4 * h; }
; #define D_COMPUTE(BUF) { D_MMA1(BUF, 0) D_MMA1(BUF, 1) D_MMA1(BUF, 2) D_MMA1(BUF, 3) }
; template <bool RESCALE, bool SWAP>
; DI void gemm_mainloop_glds(const bf16_t* __restrict__ A, const bf16_t* __restrict__ Bt, int m0, int n0, char* lds,
;                            f32x16 (&acc)[2][2], const float* ratio_lds) {
;     ...
;   for (int kt = 0; kt < NK; kt += 2) {
;     D_ISSUE(1, kt + 1);
;     if (RESCALE) {
;       if (kt == NK / 2) {
;         if (SWAP) {
;           const float sc0_ = ratio_lds[64 * wm + l31], sc1_ = ratio_lds[64 * wm + 32 + l31];
; #pragma unroll
;           for (int r = 0; r < 16; ++r) { c00[r] *= sc0_; c10[r] *= sc0_; c01[r] *= sc1_; c11[r] *= sc1_; }
;         } else {
; #pragma unroll
;           for (int r = 0; r < 16; ++r) {
;             float sc0_ = ratio_lds[64 * wm + crow(r, h)], sc1_ = ratio_lds[64 * wm + 32 + crow(r, h)];
;             c00[r] *= sc0_; c01[r] *= sc0_; c10[r] *= sc1_; c11[r] *= sc1_;
;           }
;         }
;       }
;     }
;     D_COMPUTE(0);
;     __syncthreads();
;     if (kt + 2 < NK) D_ISSUE(0, kt + 2);
;     D_COMPUTE(1);
;     __syncthreads();
;   }
;   acc[0][0] = c00; acc[0][1] = c01; acc[1][0] = c10; acc[1][1] = c11;
	s_add_i32 s1, s1, 2
	s_cmp_lt_u32 s1, 14
	s_cbranch_scc1 .Lgm_pq_loop
	ds_read_b128 v[184:187], v109
	ds_read_b128 v[188:191], v109 offset:4096
	ds_read_b128 v[192:195], v113 offset:16384
	ds_read_b128 v[196:199], v113 offset:20480
	ds_read_b128 v[200:203], v110
	ds_read_b128 v[204:207], v110 offset:4096
	ds_read_b128 v[208:211], v115 offset:16384
	ds_read_b128 v[212:215], v115 offset:20480
	ds_read_b128 v[216:219], v111
	ds_read_b128 v[220:223], v111 offset:4096
	ds_read_b128 v[224:227], v116 offset:16384
	ds_read_b128 v[228:231], v116 offset:20480
	ds_read_b128 v[232:235], v112
	ds_read_b128 v[236:239], v112 offset:4096
	ds_read_b128 v[240:243], v117 offset:16384
	ds_read_b128 v[244:247], v117 offset:20480
	s_waitcnt lgkmcnt(0)
	v_mfma_f32_32x32x16_bf16 v[0:15], v[192:195], v[184:187], v[0:15]
	v_mfma_f32_32x32x16_bf16 v[16:31], v[192:195], v[188:191], v[16:31]
	v_mfma_f32_32x32x16_bf16 v[32:47], v[196:199], v[184:187], v[32:47]
	v_mfma_f32_32x32x16_bf16 v[48:63], v[196:199], v[188:191], v[48:63]
	v_mfma_f32_32x32x16_bf16 v[0:15], v[208:211], v[200:203], v[0:15]
	v_mfma_f32_32x32x16_bf16 v[16:31], v[208:211], v[204:207], v[16:31]
	v_mfma_f32_32x32x16_bf16 v[32:47], v[212:215], v[200:203], v[32:47]
	v_mfma_f32_32x32x16_bf16 v[48:63], v[212:215], v[204:207], v[48:63]
	v_mfma_f32_32x32x16_bf16 v[0:15], v[224:227], v[216:219], v[0:15]
	v_mfma_f32_32x32x16_bf16 v[16:31], v[224:227], v[220:223], v[16:31]
	v_mfma_f32_32x32x16_bf16 v[32:47], v[228:231], v[216:219], v[32:47]
	v_mfma_f32_32x32x16_bf16 v[48:63], v[228:231], v[220:223], v[48:63]
	v_mfma_f32_32x32x16_bf16 v[0:15], v[240:243], v[232:235], v[0:15]
	v_mfma_f32_32x32x16_bf16 v[16:31], v[240:243], v[236:239], v[16:31]
	v_mfma_f32_32x32x16_bf16 v[32:47], v[244:247], v[232:235], v[32:47]
	v_mfma_f32_32x32x16_bf16 v[48:63], v[244:247], v[236:239], v[48:63]
	s_waitcnt vmcnt(0)
	s_barrier
	ds_read_b128 v[184:187], v109 offset:32768
	ds_read_b128 v[188:191], v109 offset:36864
	ds_read_b128 v[192:195], v113 offset:49152
	ds_read_b128 v[196:199], v113 offset:53248
	ds_read_b128 v[200:203], v110 offset:32768
	ds_read_b128 v[204:207], v110 offset:36864
	ds_read_b128 v[208:211], v115 offset:49152
	ds_read_b128 v[212:215], v115 offset:53248
	ds_read_b128 v[216:219], v111 offset:32768
	ds_read_b128 v[220:223], v111 offset:36864
	ds_read_b128 v[224:227], v116 offset:49152
	ds_read_b128 v[228:231], v116 offset:53248
	ds_read_b128 v[232:235], v112 offset:32768
	ds_read_b128 v[236:239], v112 offset:36864
	ds_read_b128 v[240:243], v117 offset:49152
	ds_read_b128 v[244:247], v117 offset:53248
	s_waitcnt lgkmcnt(0)
	s_barrier
	v_mfma_f32_32x32x16_bf16 v[0:15], v[192:195], v[184:187], v[0:15]
	v_mfma_f32_32x32x16_bf16 v[16:31], v[192:195], v[188:191], v[16:31]
	v_mfma_f32_32x32x16_bf16 v[32:47], v[196:199], v[184:187], v[32:47]
	v_mfma_f32_32x32x16_bf16 v[48:63], v[196:199], v[188:191], v[48:63]
	v_mfma_f32_32x32x16_bf16 v[0:15], v[208:211], v[200:203], v[0:15]
	v_mfma_f32_32x32x16_bf16 v[16:31], v[208:211], v[204:207], v[16:31]
	v_mfma_f32_32x32x16_bf16 v[32:47], v[212:215], v[200:203], v[32:47]
	v_mfma_f32_32x32x16_bf16 v[48:63], v[212:215], v[204:207], v[48:63]
	v_mfma_f32_32x32x16_bf16 v[0:15], v[224:227], v[216:219], v[0:15]
	v_mfma_f32_32x32x16_bf16 v[16:31], v[224:227], v[220:223], v[16:31]
	v_mfma_f32_32x32x16_bf16 v[32:47], v[228:231], v[216:219], v[32:47]
	v_mfma_f32_32x32x16_bf16 v[48:63], v[228:231], v[220:223], v[48:63]
	v_mfma_f32_32x32x16_bf16 v[0:15], v[240:243], v[232:235], v[0:15]
	v_mfma_f32_32x32x16_bf16 v[16:31], v[240:243], v[236:239], v[16:31]
	v_mfma_f32_32x32x16_bf16 v[32:47], v[244:247], v[232:235], v[32:47]
	v_mfma_f32_32x32x16_bf16 v[48:63], v[244:247], v[236:239], v[48:63]
	s_nop 7
	s_nop 7
	s_setprio 0
